# P3 row pass rewritten: all 16-row block loads issued up front, counted vmcnt waits, rope/rstd batched per block
# speedup vs baseline: 1.0186x; 1.0186x over previous
.Lp3_begin:
	v_and_b32_e32 v0, 63, v0
	v_readlane_b32 s20, v254, 21
	v_readlane_b32 s34, v254, 37
	v_readlane_b32 s35, v254, 38
	v_readlane_b32 s38, v254, 39
	v_readlane_b32 s39, v254, 40
	v_lshlrev_b32_e32 v1, 4, v0
	v_lshlrev_b32_e32 v2, 5, v0
	v_lshlrev_b32_e32 v9, 2, v0
	s_lshl_b32 s20, s20, 4
	s_lshl_b32 s21, s90, 7
	s_add_u32 s36, s34, 0x1000
	s_addc_u32 s37, s35, 0
	v_lshrrev_b32_e32 v3, 4, v0
	v_and_b32_e32 v6, 15, v0
	v_mul_u32_u24_e32 v3, 0x1200, v3
	v_lshl_add_u32 v6, v6, 4, v3
	v_lshrrev_b32_e32 v3, 2, v0
	v_and_b32_e32 v7, 3, v0
	v_mul_u32_u24_e32 v3, 0x1200, v3
	v_lshl_add_u32 v7, v7, 3, v3
	v_cmp_gt_u32_e32 vcc, 32, v0
	v_mov_b32_e32 v3, 0x3e000000
	s_nop 0
	v_cndmask_b32_e64 v4, v3, 1.0, vcc
	v_mov_b32_e32 v5, v4
	v_and_b32_e32 v3, 31, v0
	v_lshrrev_b32_e32 v3, 3, v3
	v_lshlrev_b32_e32 v3, 19, v3
	v_and_b32_e32 v8, 7, v0
	v_lshl_add_u32 v8, v8, 4, v3
	v_mov_b32_e32 v3, 0x1000000
	s_nop 0
	v_cndmask_b32_e64 v3, v3, 0, vcc
	v_add_u32_e32 v8, v8, v3
	global_load_dwordx4 v[18:21], v2, s[34:35]
	global_load_dwordx4 v[22:25], v2, s[34:35] offset:16
	global_load_dwordx4 v[26:29], v2, s[34:35] offset:2048
	global_load_dwordx4 v[30:33], v2, s[34:35] offset:2064
	global_load_dwordx4 v[34:37], v2, s[36:37]
	global_load_dwordx4 v[38:41], v2, s[36:37] offset:16
	global_load_dwordx4 v[42:45], v2, s[36:37] offset:2048
	global_load_dwordx4 v[46:49], v2, s[36:37] offset:2064
	global_load_dwordx4 v[10:13], v2, s[38:39]
	global_load_dwordx4 v[14:17], v2, s[38:39] offset:16
.Lp3_block:
	s_mul_i32 s0, s20, 0x1200
	s_add_u32 s4, s82, 0x7000000
	s_addc_u32 s5, s83, 0
	s_add_u32 s4, s4, s0
	s_addc_u32 s5, s5, 0
	s_and_b32 s22, s20, 0xfff
	s_cmp_eq_u32 s22, 0
	s_cselect_b32 s0, 0, 0x3600
	s_sub_u32 s6, s4, s0
	s_subb_u32 s7, s5, 0
	s_lshl_b32 s0, s20, 6
	s_add_u32 s8, s82, 0x100000
	s_addc_u32 s9, s83, 0
	s_add_u32 s8, s8, s0
	s_addc_u32 s9, s9, 0
	s_add_u32 s10, s82, 0x300000
	s_addc_u32 s11, s83, 0
	s_add_u32 s10, s10, s0
	s_addc_u32 s11, s11, 0
	s_add_u32 s24, s82, 0x2a00000
	s_addc_u32 s25, s83, 0
	s_add_u32 s24, s24, s0
	s_addc_u32 s25, s25, 0
	s_lshl_b32 s0, s20, 2
	s_add_u32 s26, s82, 0x500000
	s_addc_u32 s27, s83, 0
	s_add_u32 s26, s26, s0
	s_addc_u32 s27, s27, 0
	s_add_u32 s28, s82, 0x540000
	s_addc_u32 s29, s83, 0
	s_add_u32 s28, s28, s0
	s_addc_u32 s29, s29, 0
	s_lshr_b32 s0, s20, 12
	s_mul_i32 s0, s0, 0x3000
	s_add_u32 s0, s0, s20
	s_lshl_b32 s0, s0, 7
	s_add_u32 s30, s82, 0x17000000
	s_addc_u32 s31, s83, 0
	s_add_u32 s30, s30, s0
	s_addc_u32 s31, s31, 0
	global_load_dwordx4 v[54:57], v1, s[6:7] offset:1344
	s_add_u32 s6, s6, 0x1200
	s_addc_u32 s7, s7, 0
	global_load_dwordx4 v[62:65], v1, s[6:7] offset:1344
	s_add_u32 s6, s6, 0x1200
	s_addc_u32 s7, s7, 0
	global_load_dwordx4 v[70:73], v1, s[6:7] offset:1344
	global_load_dwordx2 v[224:225], v7, s[4:5] offset:1280
	global_load_dwordx2 v[226:227], v7, s[4:5] offset:1312
	global_load_dwordx4 v[228:231], v1, s[8:9]
	global_load_dwordx4 v[232:235], v1, s[10:11]
	global_load_dwordx4 v[202:205], v6, s[4:5] offset:1024
	global_load_dwordx4 v[74:77], v1, s[4:5]
	global_load_dwordx4 v[78:81], v1, s[4:5] offset:1344
	s_add_u32 s4, s4, 0x1200
	s_addc_u32 s5, s5, 0
	global_load_dwordx4 v[82:85], v1, s[4:5]
	global_load_dwordx4 v[86:89], v1, s[4:5] offset:1344
	s_add_u32 s4, s4, 0x1200
	s_addc_u32 s5, s5, 0
	global_load_dwordx4 v[90:93], v1, s[4:5]
	global_load_dwordx4 v[94:97], v1, s[4:5] offset:1344
	s_add_u32 s4, s4, 0x1200
	s_addc_u32 s5, s5, 0
	global_load_dwordx4 v[98:101], v1, s[4:5]
	global_load_dwordx4 v[102:105], v1, s[4:5] offset:1344
	s_add_u32 s4, s4, 0x1200
	s_addc_u32 s5, s5, 0
	global_load_dwordx4 v[206:209], v6, s[4:5] offset:1024
	global_load_dwordx4 v[106:109], v1, s[4:5]
	global_load_dwordx4 v[110:113], v1, s[4:5] offset:1344
	s_add_u32 s4, s4, 0x1200
	s_addc_u32 s5, s5, 0
	global_load_dwordx4 v[114:117], v1, s[4:5]
	global_load_dwordx4 v[118:121], v1, s[4:5] offset:1344
	s_add_u32 s4, s4, 0x1200
	s_addc_u32 s5, s5, 0
	global_load_dwordx4 v[122:125], v1, s[4:5]
	global_load_dwordx4 v[126:129], v1, s[4:5] offset:1344
	s_add_u32 s4, s4, 0x1200
	s_addc_u32 s5, s5, 0
	global_load_dwordx4 v[130:133], v1, s[4:5]
	global_load_dwordx4 v[134:137], v1, s[4:5] offset:1344
	s_add_u32 s4, s4, 0x1200
	s_addc_u32 s5, s5, 0
	global_load_dwordx4 v[210:213], v6, s[4:5] offset:1024
	global_load_dwordx4 v[138:141], v1, s[4:5]
	global_load_dwordx4 v[142:145], v1, s[4:5] offset:1344
	s_add_u32 s4, s4, 0x1200
	s_addc_u32 s5, s5, 0
	global_load_dwordx4 v[146:149], v1, s[4:5]
	global_load_dwordx4 v[150:153], v1, s[4:5] offset:1344
	s_add_u32 s4, s4, 0x1200
	s_addc_u32 s5, s5, 0
	global_load_dwordx4 v[154:157], v1, s[4:5]
	global_load_dwordx4 v[158:161], v1, s[4:5] offset:1344
	s_add_u32 s4, s4, 0x1200
	s_addc_u32 s5, s5, 0
	global_load_dwordx4 v[162:165], v1, s[4:5]
	global_load_dwordx4 v[166:169], v1, s[4:5] offset:1344
	s_add_u32 s4, s4, 0x1200
	s_addc_u32 s5, s5, 0
	global_load_dwordx4 v[214:217], v6, s[4:5] offset:1024
	global_load_dwordx4 v[170:173], v1, s[4:5]
	global_load_dwordx4 v[174:177], v1, s[4:5] offset:1344
	s_add_u32 s4, s4, 0x1200
	s_addc_u32 s5, s5, 0
	global_load_dwordx4 v[178:181], v1, s[4:5]
	global_load_dwordx4 v[182:185], v1, s[4:5] offset:1344
	s_add_u32 s4, s4, 0x1200
	s_addc_u32 s5, s5, 0
	global_load_dwordx4 v[186:189], v1, s[4:5]
	global_load_dwordx4 v[190:193], v1, s[4:5] offset:1344
	s_add_u32 s4, s4, 0x1200
	s_addc_u32 s5, s5, 0
	global_load_dwordx4 v[194:197], v1, s[4:5]
	global_load_dwordx4 v[198:201], v1, s[4:5] offset:1344
	v_mov_b32_e32 v218, 0
	v_mov_b32_e32 v219, 0
	v_mov_b32_e32 v220, 0
	v_mov_b32_e32 v221, 0
	v_mov_b32_e32 v222, 0
	s_waitcnt vmcnt(36)
	v_lshlrev_b32_e32 v244, 16, v224
	v_and_b32_e32 v245, 0xffff0000, v224
	v_lshlrev_b32_e32 v246, 16, v225
	v_and_b32_e32 v247, 0xffff0000, v225
	v_lshlrev_b32_e32 v248, 16, v226
	v_and_b32_e32 v249, 0xffff0000, v226
	v_lshlrev_b32_e32 v250, 16, v227
	v_and_b32_e32 v251, 0xffff0000, v227
	v_mul_f32_e32 v236, v248, v232
	v_mul_f32_e32 v237, v244, v232
	v_mul_f32_e32 v238, v249, v233
	v_mul_f32_e32 v239, v245, v233
	v_mul_f32_e32 v240, v250, v234
	v_mul_f32_e32 v241, v246, v234
	v_mul_f32_e32 v242, v251, v235
	v_mul_f32_e32 v243, v247, v235
	v_fma_f32 v236, v244, v228, -v236
	v_fma_f32 v237, v248, v228, v237
	v_fma_f32 v238, v245, v229, -v238
	v_fma_f32 v239, v249, v229, v239
	v_fma_f32 v240, v246, v230, -v240
	v_fma_f32 v241, v250, v230, v241
	v_fma_f32 v242, v247, v231, -v242
	v_fma_f32 v243, v251, v231, v243
	v_cvt_pk_bf16_f32 v244, v236, v237
	v_cvt_pk_bf16_f32 v245, v238, v239
	v_cvt_pk_bf16_f32 v246, v240, v241
	v_cvt_pk_bf16_f32 v247, v242, v243
	global_store_dwordx4 v1, v[244:247], s[24:25]
	s_waitcnt vmcnt(34)
	s_cmp_lg_u32 s22, 0
	s_cbranch_scc1 .Lp3_prev_ok
	v_mov_b32_e32 v54, 0
	v_mov_b32_e32 v55, 0
	v_mov_b32_e32 v56, 0
	v_mov_b32_e32 v57, 0
	v_mov_b32_e32 v62, 0
	v_mov_b32_e32 v63, 0
	v_mov_b32_e32 v64, 0
	v_mov_b32_e32 v65, 0
	v_mov_b32_e32 v70, 0
	v_mov_b32_e32 v71, 0
	v_mov_b32_e32 v72, 0
	v_mov_b32_e32 v73, 0
.Lp3_prev_ok:
	v_lshlrev_b32_e32 v50, 16, v54
	v_and_b32_e32 v51, 0xffff0000, v54
	v_lshlrev_b32_e32 v52, 16, v55
	v_and_b32_e32 v53, 0xffff0000, v55
	v_lshlrev_b32_e32 v54, 16, v56
	v_and_b32_e32 v55, 0xffff0000, v56
	v_lshlrev_b32_e32 v56, 16, v57
	v_and_b32_e32 v57, 0xffff0000, v57
	v_lshlrev_b32_e32 v58, 16, v62
	v_and_b32_e32 v59, 0xffff0000, v62
	v_lshlrev_b32_e32 v60, 16, v63
	v_and_b32_e32 v61, 0xffff0000, v63
	v_lshlrev_b32_e32 v62, 16, v64
	v_and_b32_e32 v63, 0xffff0000, v64
	v_lshlrev_b32_e32 v64, 16, v65
	v_and_b32_e32 v65, 0xffff0000, v65
	v_lshlrev_b32_e32 v66, 16, v70
	v_and_b32_e32 v67, 0xffff0000, v70
	v_lshlrev_b32_e32 v68, 16, v71
	v_and_b32_e32 v69, 0xffff0000, v71
	v_lshlrev_b32_e32 v70, 16, v72
	v_and_b32_e32 v71, 0xffff0000, v72
	v_lshlrev_b32_e32 v72, 16, v73
	v_and_b32_e32 v73, 0xffff0000, v73
	v_lshlrev_b32_e32 v244, 16, v202
	v_and_b32_e32 v245, 0xffff0000, v202
	v_lshlrev_b32_e32 v246, 16, v203
	v_and_b32_e32 v247, 0xffff0000, v203
	v_lshlrev_b32_e32 v248, 16, v204
	v_and_b32_e32 v249, 0xffff0000, v204
	v_lshlrev_b32_e32 v250, 16, v205
	v_and_b32_e32 v251, 0xffff0000, v205
	v_mul_f32_e32 v253, v244, v244
	v_fmac_f32_e32 v253, v245, v245
	v_fmac_f32_e32 v253, v246, v246
	v_fmac_f32_e32 v253, v247, v247
	v_fmac_f32_e32 v253, v248, v248
	v_fmac_f32_e32 v253, v249, v249
	v_fmac_f32_e32 v253, v250, v250
	v_fmac_f32_e32 v253, v251, v251
	s_nop 1
	v_add_f32_dpp v253, v253, v253 quad_perm:[1,0,3,2] row_mask:0xf bank_mask:0xf bound_ctrl:1
	s_nop 1
	v_add_f32_dpp v253, v253, v253 quad_perm:[2,3,0,1] row_mask:0xf bank_mask:0xf bound_ctrl:1
	s_nop 1
	v_add_f32_dpp v253, v253, v253 row_half_mirror row_mask:0xf bank_mask:0xf bound_ctrl:1
	s_nop 1
	v_add_f32_dpp v253, v253, v253 row_mirror row_mask:0xf bank_mask:0xf bound_ctrl:1
	v_lshlrev_b32_e32 v244, 16, v74
	v_and_b32_e32 v245, 0xffff0000, v74
	v_lshlrev_b32_e32 v246, 16, v75
	v_and_b32_e32 v247, 0xffff0000, v75
	v_lshlrev_b32_e32 v248, 16, v76
	v_and_b32_e32 v249, 0xffff0000, v76
	v_lshlrev_b32_e32 v250, 16, v77
	v_and_b32_e32 v251, 0xffff0000, v77
	v_mul_f32_e32 v252, v244, v244
	v_fmac_f32_e32 v252, v245, v245
	v_fmac_f32_e32 v252, v246, v246
	v_fmac_f32_e32 v252, v247, v247
	v_fmac_f32_e32 v252, v248, v248
	v_fmac_f32_e32 v252, v249, v249
	v_fmac_f32_e32 v252, v250, v250
	v_fmac_f32_e32 v252, v251, v251
	s_nop 1
	v_add_f32_dpp v252, v252, v252 quad_perm:[1,0,3,2] row_mask:0xf bank_mask:0xf bound_ctrl:1
	s_nop 1
	v_add_f32_dpp v252, v252, v252 quad_perm:[2,3,0,1] row_mask:0xf bank_mask:0xf bound_ctrl:1
	s_nop 1
	v_add_f32_dpp v252, v252, v252 row_half_mirror row_mask:0xf bank_mask:0xf bound_ctrl:1
	s_nop 1
	v_add_f32_dpp v252, v252, v252 row_mirror row_mask:0xf bank_mask:0xf bound_ctrl:1
	v_lshlrev_b32_e32 v74, 16, v78
	v_and_b32_e32 v75, 0xffff0000, v78
	v_lshlrev_b32_e32 v76, 16, v79
	v_and_b32_e32 v77, 0xffff0000, v79
	v_lshlrev_b32_e32 v78, 16, v80
	v_and_b32_e32 v79, 0xffff0000, v80
	v_lshlrev_b32_e32 v80, 16, v81
	v_and_b32_e32 v81, 0xffff0000, v81
	s_nop 0
	v_readlane_b32 s40, v252, 0
	v_readlane_b32 s41, v252, 16
	v_readlane_b32 s42, v252, 32
	v_readlane_b32 s43, v252, 48
	v_readlane_b32 s44, v253, 0
	v_pk_fma_f32 v[236:237], v[50:51], v[18:19], v[10:11]
	v_pk_fma_f32 v[238:239], v[52:53], v[20:21], v[12:13]
	v_pk_fma_f32 v[240:241], v[54:55], v[22:23], v[14:15]
	v_pk_fma_f32 v[242:243], v[56:57], v[24:25], v[16:17]
	v_pk_fma_f32 v[236:237], v[58:59], v[26:27], v[236:237]
	v_pk_fma_f32 v[238:239], v[60:61], v[28:29], v[238:239]
	v_pk_fma_f32 v[240:241], v[62:63], v[30:31], v[240:241]
	v_pk_fma_f32 v[242:243], v[64:65], v[32:33], v[242:243]
	v_pk_fma_f32 v[236:237], v[66:67], v[34:35], v[236:237]
	v_pk_fma_f32 v[238:239], v[68:69], v[36:37], v[238:239]
	v_pk_fma_f32 v[240:241], v[70:71], v[38:39], v[240:241]
	v_pk_fma_f32 v[242:243], v[72:73], v[40:41], v[242:243]
	v_pk_fma_f32 v[236:237], v[74:75], v[42:43], v[236:237]
	v_pk_fma_f32 v[238:239], v[76:77], v[44:45], v[238:239]
	v_pk_fma_f32 v[240:241], v[78:79], v[46:47], v[240:241]
	v_pk_fma_f32 v[242:243], v[80:81], v[48:49], v[242:243]
	v_writelane_b32 v218, s40, 0
	v_writelane_b32 v219, s41, 0
	v_writelane_b32 v220, s42, 0
	v_writelane_b32 v221, s43, 0
	v_writelane_b32 v222, s44, 0
	v_mul_f32_e32 v244, 0xbfb8aa3b, v236
	v_mul_f32_e32 v245, 0xbfb8aa3b, v237
	v_mul_f32_e32 v246, 0xbfb8aa3b, v238
	v_mul_f32_e32 v247, 0xbfb8aa3b, v239
	v_mul_f32_e32 v248, 0xbfb8aa3b, v240
	v_mul_f32_e32 v249, 0xbfb8aa3b, v241
	v_mul_f32_e32 v250, 0xbfb8aa3b, v242
	v_mul_f32_e32 v251, 0xbfb8aa3b, v243
	v_exp_f32_e32 v244, v244
	v_exp_f32_e32 v245, v245
	v_exp_f32_e32 v246, v246
	v_exp_f32_e32 v247, v247
	v_exp_f32_e32 v248, v248
	v_exp_f32_e32 v249, v249
	v_exp_f32_e32 v250, v250
	v_exp_f32_e32 v251, v251
	v_add_f32_e32 v244, 1.0, v244
	v_add_f32_e32 v245, 1.0, v245
	v_add_f32_e32 v246, 1.0, v246
	v_add_f32_e32 v247, 1.0, v247
	v_add_f32_e32 v248, 1.0, v248
	v_add_f32_e32 v249, 1.0, v249
	v_add_f32_e32 v250, 1.0, v250
	v_add_f32_e32 v251, 1.0, v251
	v_rcp_f32_e32 v244, v244
	v_rcp_f32_e32 v245, v245
	v_rcp_f32_e32 v246, v246
	v_rcp_f32_e32 v247, v247
	v_rcp_f32_e32 v248, v248
	v_rcp_f32_e32 v249, v249
	v_rcp_f32_e32 v250, v250
	v_rcp_f32_e32 v251, v251
	v_pk_mul_f32 v[236:237], v[236:237], v[244:245]
	v_pk_mul_f32 v[238:239], v[238:239], v[246:247]
	v_pk_mul_f32 v[240:241], v[240:241], v[248:249]
	v_pk_mul_f32 v[242:243], v[242:243], v[250:251]
	v_pk_mul_f32 v[236:237], v[4:5], v[236:237]
	v_pk_mul_f32 v[238:239], v[4:5], v[238:239]
	v_pk_mul_f32 v[240:241], v[4:5], v[240:241]
	v_pk_mul_f32 v[242:243], v[4:5], v[242:243]
	v_cvt_pk_bf16_f32 v224, v236, v237
	v_cvt_pk_bf16_f32 v225, v238, v239
	v_cvt_pk_bf16_f32 v226, v240, v241
	v_cvt_pk_bf16_f32 v227, v242, v243
	global_store_dwordx4 v8, v[224:227], s[30:31]
	s_waitcnt vmcnt(33)
	v_lshlrev_b32_e32 v244, 16, v82
	v_and_b32_e32 v245, 0xffff0000, v82
	v_lshlrev_b32_e32 v246, 16, v83
	v_and_b32_e32 v247, 0xffff0000, v83
	v_lshlrev_b32_e32 v248, 16, v84
	v_and_b32_e32 v249, 0xffff0000, v84
	v_lshlrev_b32_e32 v250, 16, v85
	v_and_b32_e32 v251, 0xffff0000, v85
	v_mul_f32_e32 v252, v244, v244
	v_fmac_f32_e32 v252, v245, v245
	v_fmac_f32_e32 v252, v246, v246
	v_fmac_f32_e32 v252, v247, v247
	v_fmac_f32_e32 v252, v248, v248
	v_fmac_f32_e32 v252, v249, v249
	v_fmac_f32_e32 v252, v250, v250
	v_fmac_f32_e32 v252, v251, v251
	s_nop 1
	v_add_f32_dpp v252, v252, v252 quad_perm:[1,0,3,2] row_mask:0xf bank_mask:0xf bound_ctrl:1
	s_nop 1
	v_add_f32_dpp v252, v252, v252 quad_perm:[2,3,0,1] row_mask:0xf bank_mask:0xf bound_ctrl:1
	s_nop 1
	v_add_f32_dpp v252, v252, v252 row_half_mirror row_mask:0xf bank_mask:0xf bound_ctrl:1
	s_nop 1
	v_add_f32_dpp v252, v252, v252 row_mirror row_mask:0xf bank_mask:0xf bound_ctrl:1
	v_lshlrev_b32_e32 v82, 16, v86
	v_and_b32_e32 v83, 0xffff0000, v86
	v_lshlrev_b32_e32 v84, 16, v87
	v_and_b32_e32 v85, 0xffff0000, v87
	v_lshlrev_b32_e32 v86, 16, v88
	v_and_b32_e32 v87, 0xffff0000, v88
	v_lshlrev_b32_e32 v88, 16, v89
	v_and_b32_e32 v89, 0xffff0000, v89
	s_nop 0
	v_readlane_b32 s40, v252, 0
	v_readlane_b32 s41, v252, 16
	v_readlane_b32 s42, v252, 32
	v_readlane_b32 s43, v252, 48
	v_readlane_b32 s44, v253, 16
	v_pk_fma_f32 v[236:237], v[58:59], v[18:19], v[10:11]
	v_pk_fma_f32 v[238:239], v[60:61], v[20:21], v[12:13]
	v_pk_fma_f32 v[240:241], v[62:63], v[22:23], v[14:15]
	v_pk_fma_f32 v[242:243], v[64:65], v[24:25], v[16:17]
	v_pk_fma_f32 v[236:237], v[66:67], v[26:27], v[236:237]
	v_pk_fma_f32 v[238:239], v[68:69], v[28:29], v[238:239]
	v_pk_fma_f32 v[240:241], v[70:71], v[30:31], v[240:241]
	v_pk_fma_f32 v[242:243], v[72:73], v[32:33], v[242:243]
	v_pk_fma_f32 v[236:237], v[74:75], v[34:35], v[236:237]
	v_pk_fma_f32 v[238:239], v[76:77], v[36:37], v[238:239]
	v_pk_fma_f32 v[240:241], v[78:79], v[38:39], v[240:241]
	v_pk_fma_f32 v[242:243], v[80:81], v[40:41], v[242:243]
	v_pk_fma_f32 v[236:237], v[82:83], v[42:43], v[236:237]
	v_pk_fma_f32 v[238:239], v[84:85], v[44:45], v[238:239]
	v_pk_fma_f32 v[240:241], v[86:87], v[46:47], v[240:241]
	v_pk_fma_f32 v[242:243], v[88:89], v[48:49], v[242:243]
	v_writelane_b32 v218, s40, 1
	v_writelane_b32 v219, s41, 1
	v_writelane_b32 v220, s42, 1
	v_writelane_b32 v221, s43, 1
	v_writelane_b32 v222, s44, 1
	v_mul_f32_e32 v244, 0xbfb8aa3b, v236
	v_mul_f32_e32 v245, 0xbfb8aa3b, v237
	v_mul_f32_e32 v246, 0xbfb8aa3b, v238
	v_mul_f32_e32 v247, 0xbfb8aa3b, v239
	v_mul_f32_e32 v248, 0xbfb8aa3b, v240
	v_mul_f32_e32 v249, 0xbfb8aa3b, v241
	v_mul_f32_e32 v250, 0xbfb8aa3b, v242
	v_mul_f32_e32 v251, 0xbfb8aa3b, v243
	v_exp_f32_e32 v244, v244
	v_exp_f32_e32 v245, v245
	v_exp_f32_e32 v246, v246
	v_exp_f32_e32 v247, v247
	v_exp_f32_e32 v248, v248
	v_exp_f32_e32 v249, v249
	v_exp_f32_e32 v250, v250
	v_exp_f32_e32 v251, v251
	v_add_f32_e32 v244, 1.0, v244
	v_add_f32_e32 v245, 1.0, v245
	v_add_f32_e32 v246, 1.0, v246
	v_add_f32_e32 v247, 1.0, v247
	v_add_f32_e32 v248, 1.0, v248
	v_add_f32_e32 v249, 1.0, v249
	v_add_f32_e32 v250, 1.0, v250
	v_add_f32_e32 v251, 1.0, v251
	v_rcp_f32_e32 v244, v244
	v_rcp_f32_e32 v245, v245
	v_rcp_f32_e32 v246, v246
	v_rcp_f32_e32 v247, v247
	v_rcp_f32_e32 v248, v248
	v_rcp_f32_e32 v249, v249
	v_rcp_f32_e32 v250, v250
	v_rcp_f32_e32 v251, v251
	v_pk_mul_f32 v[236:237], v[236:237], v[244:245]
	v_pk_mul_f32 v[238:239], v[238:239], v[246:247]
	v_pk_mul_f32 v[240:241], v[240:241], v[248:249]
	v_pk_mul_f32 v[242:243], v[242:243], v[250:251]
	v_pk_mul_f32 v[236:237], v[4:5], v[236:237]
	v_pk_mul_f32 v[238:239], v[4:5], v[238:239]
	v_pk_mul_f32 v[240:241], v[4:5], v[240:241]
	v_pk_mul_f32 v[242:243], v[4:5], v[242:243]
	v_cvt_pk_bf16_f32 v228, v236, v237
	v_cvt_pk_bf16_f32 v229, v238, v239
	v_cvt_pk_bf16_f32 v230, v240, v241
	v_cvt_pk_bf16_f32 v231, v242, v243
	global_store_dwordx4 v8, v[228:231], s[30:31] offset:128
	s_waitcnt vmcnt(32)
	v_lshlrev_b32_e32 v244, 16, v90
	v_and_b32_e32 v245, 0xffff0000, v90
	v_lshlrev_b32_e32 v246, 16, v91
	v_and_b32_e32 v247, 0xffff0000, v91
	v_lshlrev_b32_e32 v248, 16, v92
	v_and_b32_e32 v249, 0xffff0000, v92
	v_lshlrev_b32_e32 v250, 16, v93
	v_and_b32_e32 v251, 0xffff0000, v93
	v_mul_f32_e32 v252, v244, v244
	v_fmac_f32_e32 v252, v245, v245
	v_fmac_f32_e32 v252, v246, v246
	v_fmac_f32_e32 v252, v247, v247
	v_fmac_f32_e32 v252, v248, v248
	v_fmac_f32_e32 v252, v249, v249
	v_fmac_f32_e32 v252, v250, v250
	v_fmac_f32_e32 v252, v251, v251
	s_nop 1
	v_add_f32_dpp v252, v252, v252 quad_perm:[1,0,3,2] row_mask:0xf bank_mask:0xf bound_ctrl:1
	s_nop 1
	v_add_f32_dpp v252, v252, v252 quad_perm:[2,3,0,1] row_mask:0xf bank_mask:0xf bound_ctrl:1
	s_nop 1
	v_add_f32_dpp v252, v252, v252 row_half_mirror row_mask:0xf bank_mask:0xf bound_ctrl:1
	s_nop 1
	v_add_f32_dpp v252, v252, v252 row_mirror row_mask:0xf bank_mask:0xf bound_ctrl:1
	v_lshlrev_b32_e32 v90, 16, v94
	v_and_b32_e32 v91, 0xffff0000, v94
	v_lshlrev_b32_e32 v92, 16, v95
	v_and_b32_e32 v93, 0xffff0000, v95
	v_lshlrev_b32_e32 v94, 16, v96
	v_and_b32_e32 v95, 0xffff0000, v96
	v_lshlrev_b32_e32 v96, 16, v97
	v_and_b32_e32 v97, 0xffff0000, v97
	s_nop 0
	v_readlane_b32 s40, v252, 0
	v_readlane_b32 s41, v252, 16
	v_readlane_b32 s42, v252, 32
	v_readlane_b32 s43, v252, 48
	v_readlane_b32 s44, v253, 32
	v_pk_fma_f32 v[236:237], v[66:67], v[18:19], v[10:11]
	v_pk_fma_f32 v[238:239], v[68:69], v[20:21], v[12:13]
	v_pk_fma_f32 v[240:241], v[70:71], v[22:23], v[14:15]
	v_pk_fma_f32 v[242:243], v[72:73], v[24:25], v[16:17]
	v_pk_fma_f32 v[236:237], v[74:75], v[26:27], v[236:237]
	v_pk_fma_f32 v[238:239], v[76:77], v[28:29], v[238:239]
	v_pk_fma_f32 v[240:241], v[78:79], v[30:31], v[240:241]
	v_pk_fma_f32 v[242:243], v[80:81], v[32:33], v[242:243]
	v_pk_fma_f32 v[236:237], v[82:83], v[34:35], v[236:237]
	v_pk_fma_f32 v[238:239], v[84:85], v[36:37], v[238:239]
	v_pk_fma_f32 v[240:241], v[86:87], v[38:39], v[240:241]
	v_pk_fma_f32 v[242:243], v[88:89], v[40:41], v[242:243]
	v_pk_fma_f32 v[236:237], v[90:91], v[42:43], v[236:237]
	v_pk_fma_f32 v[238:239], v[92:93], v[44:45], v[238:239]
	v_pk_fma_f32 v[240:241], v[94:95], v[46:47], v[240:241]
	v_pk_fma_f32 v[242:243], v[96:97], v[48:49], v[242:243]
	v_writelane_b32 v218, s40, 2
	v_writelane_b32 v219, s41, 2
	v_writelane_b32 v220, s42, 2
	v_writelane_b32 v221, s43, 2
	v_writelane_b32 v222, s44, 2
	v_mul_f32_e32 v244, 0xbfb8aa3b, v236
	v_mul_f32_e32 v245, 0xbfb8aa3b, v237
	v_mul_f32_e32 v246, 0xbfb8aa3b, v238
	v_mul_f32_e32 v247, 0xbfb8aa3b, v239
	v_mul_f32_e32 v248, 0xbfb8aa3b, v240
	v_mul_f32_e32 v249, 0xbfb8aa3b, v241
	v_mul_f32_e32 v250, 0xbfb8aa3b, v242
	v_mul_f32_e32 v251, 0xbfb8aa3b, v243
	v_exp_f32_e32 v244, v244
	v_exp_f32_e32 v245, v245
	v_exp_f32_e32 v246, v246
	v_exp_f32_e32 v247, v247
	v_exp_f32_e32 v248, v248
	v_exp_f32_e32 v249, v249
	v_exp_f32_e32 v250, v250
	v_exp_f32_e32 v251, v251
	v_add_f32_e32 v244, 1.0, v244
	v_add_f32_e32 v245, 1.0, v245
	v_add_f32_e32 v246, 1.0, v246
	v_add_f32_e32 v247, 1.0, v247
	v_add_f32_e32 v248, 1.0, v248
	v_add_f32_e32 v249, 1.0, v249
	v_add_f32_e32 v250, 1.0, v250
	v_add_f32_e32 v251, 1.0, v251
	v_rcp_f32_e32 v244, v244
	v_rcp_f32_e32 v245, v245
	v_rcp_f32_e32 v246, v246
	v_rcp_f32_e32 v247, v247
	v_rcp_f32_e32 v248, v248
	v_rcp_f32_e32 v249, v249
	v_rcp_f32_e32 v250, v250
	v_rcp_f32_e32 v251, v251
	v_pk_mul_f32 v[236:237], v[236:237], v[244:245]
	v_pk_mul_f32 v[238:239], v[238:239], v[246:247]
	v_pk_mul_f32 v[240:241], v[240:241], v[248:249]
	v_pk_mul_f32 v[242:243], v[242:243], v[250:251]
	v_pk_mul_f32 v[236:237], v[4:5], v[236:237]
	v_pk_mul_f32 v[238:239], v[4:5], v[238:239]
	v_pk_mul_f32 v[240:241], v[4:5], v[240:241]
	v_pk_mul_f32 v[242:243], v[4:5], v[242:243]
	v_cvt_pk_bf16_f32 v224, v236, v237
	v_cvt_pk_bf16_f32 v225, v238, v239
	v_cvt_pk_bf16_f32 v226, v240, v241
	v_cvt_pk_bf16_f32 v227, v242, v243
	global_store_dwordx4 v8, v[224:227], s[30:31] offset:256
	s_waitcnt vmcnt(31)
	v_lshlrev_b32_e32 v244, 16, v98
	v_and_b32_e32 v245, 0xffff0000, v98
	v_lshlrev_b32_e32 v246, 16, v99
	v_and_b32_e32 v247, 0xffff0000, v99
	v_lshlrev_b32_e32 v248, 16, v100
	v_and_b32_e32 v249, 0xffff0000, v100
	v_lshlrev_b32_e32 v250, 16, v101
	v_and_b32_e32 v251, 0xffff0000, v101
	v_mul_f32_e32 v252, v244, v244
	v_fmac_f32_e32 v252, v245, v245
	v_fmac_f32_e32 v252, v246, v246
	v_fmac_f32_e32 v252, v247, v247
	v_fmac_f32_e32 v252, v248, v248
	v_fmac_f32_e32 v252, v249, v249
	v_fmac_f32_e32 v252, v250, v250
	v_fmac_f32_e32 v252, v251, v251
	s_nop 1
	v_add_f32_dpp v252, v252, v252 quad_perm:[1,0,3,2] row_mask:0xf bank_mask:0xf bound_ctrl:1
	s_nop 1
	v_add_f32_dpp v252, v252, v252 quad_perm:[2,3,0,1] row_mask:0xf bank_mask:0xf bound_ctrl:1
	s_nop 1
	v_add_f32_dpp v252, v252, v252 row_half_mirror row_mask:0xf bank_mask:0xf bound_ctrl:1
	s_nop 1
	v_add_f32_dpp v252, v252, v252 row_mirror row_mask:0xf bank_mask:0xf bound_ctrl:1
	v_lshlrev_b32_e32 v98, 16, v102
	v_and_b32_e32 v99, 0xffff0000, v102
	v_lshlrev_b32_e32 v100, 16, v103
	v_and_b32_e32 v101, 0xffff0000, v103
	v_lshlrev_b32_e32 v102, 16, v104
	v_and_b32_e32 v103, 0xffff0000, v104
	v_lshlrev_b32_e32 v104, 16, v105
	v_and_b32_e32 v105, 0xffff0000, v105
	s_nop 0
	v_readlane_b32 s40, v252, 0
	v_readlane_b32 s41, v252, 16
	v_readlane_b32 s42, v252, 32
	v_readlane_b32 s43, v252, 48
	v_readlane_b32 s44, v253, 48
	v_pk_fma_f32 v[236:237], v[74:75], v[18:19], v[10:11]
	v_pk_fma_f32 v[238:239], v[76:77], v[20:21], v[12:13]
	v_pk_fma_f32 v[240:241], v[78:79], v[22:23], v[14:15]
	v_pk_fma_f32 v[242:243], v[80:81], v[24:25], v[16:17]
	v_pk_fma_f32 v[236:237], v[82:83], v[26:27], v[236:237]
	v_pk_fma_f32 v[238:239], v[84:85], v[28:29], v[238:239]
	v_pk_fma_f32 v[240:241], v[86:87], v[30:31], v[240:241]
	v_pk_fma_f32 v[242:243], v[88:89], v[32:33], v[242:243]
	v_pk_fma_f32 v[236:237], v[90:91], v[34:35], v[236:237]
	v_pk_fma_f32 v[238:239], v[92:93], v[36:37], v[238:239]
	v_pk_fma_f32 v[240:241], v[94:95], v[38:39], v[240:241]
	v_pk_fma_f32 v[242:243], v[96:97], v[40:41], v[242:243]
	v_pk_fma_f32 v[236:237], v[98:99], v[42:43], v[236:237]
	v_pk_fma_f32 v[238:239], v[100:101], v[44:45], v[238:239]
	v_pk_fma_f32 v[240:241], v[102:103], v[46:47], v[240:241]
	v_pk_fma_f32 v[242:243], v[104:105], v[48:49], v[242:243]
	v_writelane_b32 v218, s40, 3
	v_writelane_b32 v219, s41, 3
	v_writelane_b32 v220, s42, 3
	v_writelane_b32 v221, s43, 3
	v_writelane_b32 v222, s44, 3
	v_mul_f32_e32 v244, 0xbfb8aa3b, v236
	v_mul_f32_e32 v245, 0xbfb8aa3b, v237
	v_mul_f32_e32 v246, 0xbfb8aa3b, v238
	v_mul_f32_e32 v247, 0xbfb8aa3b, v239
	v_mul_f32_e32 v248, 0xbfb8aa3b, v240
	v_mul_f32_e32 v249, 0xbfb8aa3b, v241
	v_mul_f32_e32 v250, 0xbfb8aa3b, v242
	v_mul_f32_e32 v251, 0xbfb8aa3b, v243
	v_exp_f32_e32 v244, v244
	v_exp_f32_e32 v245, v245
	v_exp_f32_e32 v246, v246
	v_exp_f32_e32 v247, v247
	v_exp_f32_e32 v248, v248
	v_exp_f32_e32 v249, v249
	v_exp_f32_e32 v250, v250
	v_exp_f32_e32 v251, v251
	v_add_f32_e32 v244, 1.0, v244
	v_add_f32_e32 v245, 1.0, v245
	v_add_f32_e32 v246, 1.0, v246
	v_add_f32_e32 v247, 1.0, v247
	v_add_f32_e32 v248, 1.0, v248
	v_add_f32_e32 v249, 1.0, v249
	v_add_f32_e32 v250, 1.0, v250
	v_add_f32_e32 v251, 1.0, v251
	v_rcp_f32_e32 v244, v244
	v_rcp_f32_e32 v245, v245
	v_rcp_f32_e32 v246, v246
	v_rcp_f32_e32 v247, v247
	v_rcp_f32_e32 v248, v248
	v_rcp_f32_e32 v249, v249
	v_rcp_f32_e32 v250, v250
	v_rcp_f32_e32 v251, v251
	v_pk_mul_f32 v[236:237], v[236:237], v[244:245]
	v_pk_mul_f32 v[238:239], v[238:239], v[246:247]
	v_pk_mul_f32 v[240:241], v[240:241], v[248:249]
	v_pk_mul_f32 v[242:243], v[242:243], v[250:251]
	v_pk_mul_f32 v[236:237], v[4:5], v[236:237]
	v_pk_mul_f32 v[238:239], v[4:5], v[238:239]
	v_pk_mul_f32 v[240:241], v[4:5], v[240:241]
	v_pk_mul_f32 v[242:243], v[4:5], v[242:243]
	v_cvt_pk_bf16_f32 v228, v236, v237
	v_cvt_pk_bf16_f32 v229, v238, v239
	v_cvt_pk_bf16_f32 v230, v240, v241
	v_cvt_pk_bf16_f32 v231, v242, v243
	global_store_dwordx4 v8, v[228:231], s[30:31] offset:384
	s_waitcnt vmcnt(29)
	v_lshlrev_b32_e32 v244, 16, v206
	v_and_b32_e32 v245, 0xffff0000, v206
	v_lshlrev_b32_e32 v246, 16, v207
	v_and_b32_e32 v247, 0xffff0000, v207
	v_lshlrev_b32_e32 v248, 16, v208
	v_and_b32_e32 v249, 0xffff0000, v208
	v_lshlrev_b32_e32 v250, 16, v209
	v_and_b32_e32 v251, 0xffff0000, v209
	v_mul_f32_e32 v253, v244, v244
	v_fmac_f32_e32 v253, v245, v245
	v_fmac_f32_e32 v253, v246, v246
	v_fmac_f32_e32 v253, v247, v247
	v_fmac_f32_e32 v253, v248, v248
	v_fmac_f32_e32 v253, v249, v249
	v_fmac_f32_e32 v253, v250, v250
	v_fmac_f32_e32 v253, v251, v251
	s_nop 1
	v_add_f32_dpp v253, v253, v253 quad_perm:[1,0,3,2] row_mask:0xf bank_mask:0xf bound_ctrl:1
	s_nop 1
	v_add_f32_dpp v253, v253, v253 quad_perm:[2,3,0,1] row_mask:0xf bank_mask:0xf bound_ctrl:1
	s_nop 1
	v_add_f32_dpp v253, v253, v253 row_half_mirror row_mask:0xf bank_mask:0xf bound_ctrl:1
	s_nop 1
	v_add_f32_dpp v253, v253, v253 row_mirror row_mask:0xf bank_mask:0xf bound_ctrl:1
	v_lshlrev_b32_e32 v244, 16, v106
	v_and_b32_e32 v245, 0xffff0000, v106
	v_lshlrev_b32_e32 v246, 16, v107
	v_and_b32_e32 v247, 0xffff0000, v107
	v_lshlrev_b32_e32 v248, 16, v108
	v_and_b32_e32 v249, 0xffff0000, v108
	v_lshlrev_b32_e32 v250, 16, v109
	v_and_b32_e32 v251, 0xffff0000, v109
	v_mul_f32_e32 v252, v244, v244
	v_fmac_f32_e32 v252, v245, v245
	v_fmac_f32_e32 v252, v246, v246
	v_fmac_f32_e32 v252, v247, v247
	v_fmac_f32_e32 v252, v248, v248
	v_fmac_f32_e32 v252, v249, v249
	v_fmac_f32_e32 v252, v250, v250
	v_fmac_f32_e32 v252, v251, v251
	s_nop 1
	v_add_f32_dpp v252, v252, v252 quad_perm:[1,0,3,2] row_mask:0xf bank_mask:0xf bound_ctrl:1
	s_nop 1
	v_add_f32_dpp v252, v252, v252 quad_perm:[2,3,0,1] row_mask:0xf bank_mask:0xf bound_ctrl:1
	s_nop 1
	v_add_f32_dpp v252, v252, v252 row_half_mirror row_mask:0xf bank_mask:0xf bound_ctrl:1
	s_nop 1
	v_add_f32_dpp v252, v252, v252 row_mirror row_mask:0xf bank_mask:0xf bound_ctrl:1
	v_lshlrev_b32_e32 v106, 16, v110
	v_and_b32_e32 v107, 0xffff0000, v110
	v_lshlrev_b32_e32 v108, 16, v111
	v_and_b32_e32 v109, 0xffff0000, v111
	v_lshlrev_b32_e32 v110, 16, v112
	v_and_b32_e32 v111, 0xffff0000, v112
	v_lshlrev_b32_e32 v112, 16, v113
	v_and_b32_e32 v113, 0xffff0000, v113
	s_nop 0
	v_readlane_b32 s40, v252, 0
	v_readlane_b32 s41, v252, 16
	v_readlane_b32 s42, v252, 32
	v_readlane_b32 s43, v252, 48
	v_readlane_b32 s44, v253, 0
	v_pk_fma_f32 v[236:237], v[82:83], v[18:19], v[10:11]
	v_pk_fma_f32 v[238:239], v[84:85], v[20:21], v[12:13]
	v_pk_fma_f32 v[240:241], v[86:87], v[22:23], v[14:15]
	v_pk_fma_f32 v[242:243], v[88:89], v[24:25], v[16:17]
	v_pk_fma_f32 v[236:237], v[90:91], v[26:27], v[236:237]
	v_pk_fma_f32 v[238:239], v[92:93], v[28:29], v[238:239]
	v_pk_fma_f32 v[240:241], v[94:95], v[30:31], v[240:241]
	v_pk_fma_f32 v[242:243], v[96:97], v[32:33], v[242:243]
	v_pk_fma_f32 v[236:237], v[98:99], v[34:35], v[236:237]
	v_pk_fma_f32 v[238:239], v[100:101], v[36:37], v[238:239]
	v_pk_fma_f32 v[240:241], v[102:103], v[38:39], v[240:241]
	v_pk_fma_f32 v[242:243], v[104:105], v[40:41], v[242:243]
	v_pk_fma_f32 v[236:237], v[106:107], v[42:43], v[236:237]
	v_pk_fma_f32 v[238:239], v[108:109], v[44:45], v[238:239]
	v_pk_fma_f32 v[240:241], v[110:111], v[46:47], v[240:241]
	v_pk_fma_f32 v[242:243], v[112:113], v[48:49], v[242:243]
	v_writelane_b32 v218, s40, 4
	v_writelane_b32 v219, s41, 4
	v_writelane_b32 v220, s42, 4
	v_writelane_b32 v221, s43, 4
	v_writelane_b32 v222, s44, 4
	v_mul_f32_e32 v244, 0xbfb8aa3b, v236
	v_mul_f32_e32 v245, 0xbfb8aa3b, v237
	v_mul_f32_e32 v246, 0xbfb8aa3b, v238
	v_mul_f32_e32 v247, 0xbfb8aa3b, v239
	v_mul_f32_e32 v248, 0xbfb8aa3b, v240
	v_mul_f32_e32 v249, 0xbfb8aa3b, v241
	v_mul_f32_e32 v250, 0xbfb8aa3b, v242
	v_mul_f32_e32 v251, 0xbfb8aa3b, v243
	v_exp_f32_e32 v244, v244
	v_exp_f32_e32 v245, v245
	v_exp_f32_e32 v246, v246
	v_exp_f32_e32 v247, v247
	v_exp_f32_e32 v248, v248
	v_exp_f32_e32 v249, v249
	v_exp_f32_e32 v250, v250
	v_exp_f32_e32 v251, v251
	v_add_f32_e32 v244, 1.0, v244
	v_add_f32_e32 v245, 1.0, v245
	v_add_f32_e32 v246, 1.0, v246
	v_add_f32_e32 v247, 1.0, v247
	v_add_f32_e32 v248, 1.0, v248
	v_add_f32_e32 v249, 1.0, v249
	v_add_f32_e32 v250, 1.0, v250
	v_add_f32_e32 v251, 1.0, v251
	v_rcp_f32_e32 v244, v244
	v_rcp_f32_e32 v245, v245
	v_rcp_f32_e32 v246, v246
	v_rcp_f32_e32 v247, v247
	v_rcp_f32_e32 v248, v248
	v_rcp_f32_e32 v249, v249
	v_rcp_f32_e32 v250, v250
	v_rcp_f32_e32 v251, v251
	v_pk_mul_f32 v[236:237], v[236:237], v[244:245]
	v_pk_mul_f32 v[238:239], v[238:239], v[246:247]
	v_pk_mul_f32 v[240:241], v[240:241], v[248:249]
	v_pk_mul_f32 v[242:243], v[242:243], v[250:251]
	v_pk_mul_f32 v[236:237], v[4:5], v[236:237]
	v_pk_mul_f32 v[238:239], v[4:5], v[238:239]
	v_pk_mul_f32 v[240:241], v[4:5], v[240:241]
	v_pk_mul_f32 v[242:243], v[4:5], v[242:243]
	v_cvt_pk_bf16_f32 v224, v236, v237
	v_cvt_pk_bf16_f32 v225, v238, v239
	v_cvt_pk_bf16_f32 v226, v240, v241
	v_cvt_pk_bf16_f32 v227, v242, v243
	global_store_dwordx4 v8, v[224:227], s[30:31] offset:512
	s_waitcnt vmcnt(28)
	v_lshlrev_b32_e32 v244, 16, v114
	v_and_b32_e32 v245, 0xffff0000, v114
	v_lshlrev_b32_e32 v246, 16, v115
	v_and_b32_e32 v247, 0xffff0000, v115
	v_lshlrev_b32_e32 v248, 16, v116
	v_and_b32_e32 v249, 0xffff0000, v116
	v_lshlrev_b32_e32 v250, 16, v117
	v_and_b32_e32 v251, 0xffff0000, v117
	v_mul_f32_e32 v252, v244, v244
	v_fmac_f32_e32 v252, v245, v245
	v_fmac_f32_e32 v252, v246, v246
	v_fmac_f32_e32 v252, v247, v247
	v_fmac_f32_e32 v252, v248, v248
	v_fmac_f32_e32 v252, v249, v249
	v_fmac_f32_e32 v252, v250, v250
	v_fmac_f32_e32 v252, v251, v251
	s_nop 1
	v_add_f32_dpp v252, v252, v252 quad_perm:[1,0,3,2] row_mask:0xf bank_mask:0xf bound_ctrl:1
	s_nop 1
	v_add_f32_dpp v252, v252, v252 quad_perm:[2,3,0,1] row_mask:0xf bank_mask:0xf bound_ctrl:1
	s_nop 1
	v_add_f32_dpp v252, v252, v252 row_half_mirror row_mask:0xf bank_mask:0xf bound_ctrl:1
	s_nop 1
	v_add_f32_dpp v252, v252, v252 row_mirror row_mask:0xf bank_mask:0xf bound_ctrl:1
	v_lshlrev_b32_e32 v114, 16, v118
	v_and_b32_e32 v115, 0xffff0000, v118
	v_lshlrev_b32_e32 v116, 16, v119
	v_and_b32_e32 v117, 0xffff0000, v119
	v_lshlrev_b32_e32 v118, 16, v120
	v_and_b32_e32 v119, 0xffff0000, v120
	v_lshlrev_b32_e32 v120, 16, v121
	v_and_b32_e32 v121, 0xffff0000, v121
	s_nop 0
	v_readlane_b32 s40, v252, 0
	v_readlane_b32 s41, v252, 16
	v_readlane_b32 s42, v252, 32
	v_readlane_b32 s43, v252, 48
	v_readlane_b32 s44, v253, 16
	v_pk_fma_f32 v[236:237], v[90:91], v[18:19], v[10:11]
	v_pk_fma_f32 v[238:239], v[92:93], v[20:21], v[12:13]
	v_pk_fma_f32 v[240:241], v[94:95], v[22:23], v[14:15]
	v_pk_fma_f32 v[242:243], v[96:97], v[24:25], v[16:17]
	v_pk_fma_f32 v[236:237], v[98:99], v[26:27], v[236:237]
	v_pk_fma_f32 v[238:239], v[100:101], v[28:29], v[238:239]
	v_pk_fma_f32 v[240:241], v[102:103], v[30:31], v[240:241]
	v_pk_fma_f32 v[242:243], v[104:105], v[32:33], v[242:243]
	v_pk_fma_f32 v[236:237], v[106:107], v[34:35], v[236:237]
	v_pk_fma_f32 v[238:239], v[108:109], v[36:37], v[238:239]
	v_pk_fma_f32 v[240:241], v[110:111], v[38:39], v[240:241]
	v_pk_fma_f32 v[242:243], v[112:113], v[40:41], v[242:243]
	v_pk_fma_f32 v[236:237], v[114:115], v[42:43], v[236:237]
	v_pk_fma_f32 v[238:239], v[116:117], v[44:45], v[238:239]
	v_pk_fma_f32 v[240:241], v[118:119], v[46:47], v[240:241]
	v_pk_fma_f32 v[242:243], v[120:121], v[48:49], v[242:243]
	v_writelane_b32 v218, s40, 5
	v_writelane_b32 v219, s41, 5
	v_writelane_b32 v220, s42, 5
	v_writelane_b32 v221, s43, 5
	v_writelane_b32 v222, s44, 5
	v_mul_f32_e32 v244, 0xbfb8aa3b, v236
	v_mul_f32_e32 v245, 0xbfb8aa3b, v237
	v_mul_f32_e32 v246, 0xbfb8aa3b, v238
	v_mul_f32_e32 v247, 0xbfb8aa3b, v239
	v_mul_f32_e32 v248, 0xbfb8aa3b, v240
	v_mul_f32_e32 v249, 0xbfb8aa3b, v241
	v_mul_f32_e32 v250, 0xbfb8aa3b, v242
	v_mul_f32_e32 v251, 0xbfb8aa3b, v243
	v_exp_f32_e32 v244, v244
	v_exp_f32_e32 v245, v245
	v_exp_f32_e32 v246, v246
	v_exp_f32_e32 v247, v247
	v_exp_f32_e32 v248, v248
	v_exp_f32_e32 v249, v249
	v_exp_f32_e32 v250, v250
	v_exp_f32_e32 v251, v251
	v_add_f32_e32 v244, 1.0, v244
	v_add_f32_e32 v245, 1.0, v245
	v_add_f32_e32 v246, 1.0, v246
	v_add_f32_e32 v247, 1.0, v247
	v_add_f32_e32 v248, 1.0, v248
	v_add_f32_e32 v249, 1.0, v249
	v_add_f32_e32 v250, 1.0, v250
	v_add_f32_e32 v251, 1.0, v251
	v_rcp_f32_e32 v244, v244
	v_rcp_f32_e32 v245, v245
	v_rcp_f32_e32 v246, v246
	v_rcp_f32_e32 v247, v247
	v_rcp_f32_e32 v248, v248
	v_rcp_f32_e32 v249, v249
	v_rcp_f32_e32 v250, v250
	v_rcp_f32_e32 v251, v251
	v_pk_mul_f32 v[236:237], v[236:237], v[244:245]
	v_pk_mul_f32 v[238:239], v[238:239], v[246:247]
	v_pk_mul_f32 v[240:241], v[240:241], v[248:249]
	v_pk_mul_f32 v[242:243], v[242:243], v[250:251]
	v_pk_mul_f32 v[236:237], v[4:5], v[236:237]
	v_pk_mul_f32 v[238:239], v[4:5], v[238:239]
	v_pk_mul_f32 v[240:241], v[4:5], v[240:241]
	v_pk_mul_f32 v[242:243], v[4:5], v[242:243]
	v_cvt_pk_bf16_f32 v228, v236, v237
	v_cvt_pk_bf16_f32 v229, v238, v239
	v_cvt_pk_bf16_f32 v230, v240, v241
	v_cvt_pk_bf16_f32 v231, v242, v243
	global_store_dwordx4 v8, v[228:231], s[30:31] offset:640
	s_waitcnt vmcnt(27)
	v_lshlrev_b32_e32 v244, 16, v122
	v_and_b32_e32 v245, 0xffff0000, v122
	v_lshlrev_b32_e32 v246, 16, v123
	v_and_b32_e32 v247, 0xffff0000, v123
	v_lshlrev_b32_e32 v248, 16, v124
	v_and_b32_e32 v249, 0xffff0000, v124
	v_lshlrev_b32_e32 v250, 16, v125
	v_and_b32_e32 v251, 0xffff0000, v125
	v_mul_f32_e32 v252, v244, v244
	v_fmac_f32_e32 v252, v245, v245
	v_fmac_f32_e32 v252, v246, v246
	v_fmac_f32_e32 v252, v247, v247
	v_fmac_f32_e32 v252, v248, v248
	v_fmac_f32_e32 v252, v249, v249
	v_fmac_f32_e32 v252, v250, v250
	v_fmac_f32_e32 v252, v251, v251
	s_nop 1
	v_add_f32_dpp v252, v252, v252 quad_perm:[1,0,3,2] row_mask:0xf bank_mask:0xf bound_ctrl:1
	s_nop 1
	v_add_f32_dpp v252, v252, v252 quad_perm:[2,3,0,1] row_mask:0xf bank_mask:0xf bound_ctrl:1
	s_nop 1
	v_add_f32_dpp v252, v252, v252 row_half_mirror row_mask:0xf bank_mask:0xf bound_ctrl:1
	s_nop 1
	v_add_f32_dpp v252, v252, v252 row_mirror row_mask:0xf bank_mask:0xf bound_ctrl:1
	v_lshlrev_b32_e32 v122, 16, v126
	v_and_b32_e32 v123, 0xffff0000, v126
	v_lshlrev_b32_e32 v124, 16, v127
	v_and_b32_e32 v125, 0xffff0000, v127
	v_lshlrev_b32_e32 v126, 16, v128
	v_and_b32_e32 v127, 0xffff0000, v128
	v_lshlrev_b32_e32 v128, 16, v129
	v_and_b32_e32 v129, 0xffff0000, v129
	s_nop 0
	v_readlane_b32 s40, v252, 0
	v_readlane_b32 s41, v252, 16
	v_readlane_b32 s42, v252, 32
	v_readlane_b32 s43, v252, 48
	v_readlane_b32 s44, v253, 32
	v_pk_fma_f32 v[236:237], v[98:99], v[18:19], v[10:11]
	v_pk_fma_f32 v[238:239], v[100:101], v[20:21], v[12:13]
	v_pk_fma_f32 v[240:241], v[102:103], v[22:23], v[14:15]
	v_pk_fma_f32 v[242:243], v[104:105], v[24:25], v[16:17]
	v_pk_fma_f32 v[236:237], v[106:107], v[26:27], v[236:237]
	v_pk_fma_f32 v[238:239], v[108:109], v[28:29], v[238:239]
	v_pk_fma_f32 v[240:241], v[110:111], v[30:31], v[240:241]
	v_pk_fma_f32 v[242:243], v[112:113], v[32:33], v[242:243]
	v_pk_fma_f32 v[236:237], v[114:115], v[34:35], v[236:237]
	v_pk_fma_f32 v[238:239], v[116:117], v[36:37], v[238:239]
	v_pk_fma_f32 v[240:241], v[118:119], v[38:39], v[240:241]
	v_pk_fma_f32 v[242:243], v[120:121], v[40:41], v[242:243]
	v_pk_fma_f32 v[236:237], v[122:123], v[42:43], v[236:237]
	v_pk_fma_f32 v[238:239], v[124:125], v[44:45], v[238:239]
	v_pk_fma_f32 v[240:241], v[126:127], v[46:47], v[240:241]
	v_pk_fma_f32 v[242:243], v[128:129], v[48:49], v[242:243]
	v_writelane_b32 v218, s40, 6
	v_writelane_b32 v219, s41, 6
	v_writelane_b32 v220, s42, 6
	v_writelane_b32 v221, s43, 6
	v_writelane_b32 v222, s44, 6
	v_mul_f32_e32 v244, 0xbfb8aa3b, v236
	v_mul_f32_e32 v245, 0xbfb8aa3b, v237
	v_mul_f32_e32 v246, 0xbfb8aa3b, v238
	v_mul_f32_e32 v247, 0xbfb8aa3b, v239
	v_mul_f32_e32 v248, 0xbfb8aa3b, v240
	v_mul_f32_e32 v249, 0xbfb8aa3b, v241
	v_mul_f32_e32 v250, 0xbfb8aa3b, v242
	v_mul_f32_e32 v251, 0xbfb8aa3b, v243
	v_exp_f32_e32 v244, v244
	v_exp_f32_e32 v245, v245
	v_exp_f32_e32 v246, v246
	v_exp_f32_e32 v247, v247
	v_exp_f32_e32 v248, v248
	v_exp_f32_e32 v249, v249
	v_exp_f32_e32 v250, v250
	v_exp_f32_e32 v251, v251
	v_add_f32_e32 v244, 1.0, v244
	v_add_f32_e32 v245, 1.0, v245
	v_add_f32_e32 v246, 1.0, v246
	v_add_f32_e32 v247, 1.0, v247
	v_add_f32_e32 v248, 1.0, v248
	v_add_f32_e32 v249, 1.0, v249
	v_add_f32_e32 v250, 1.0, v250
	v_add_f32_e32 v251, 1.0, v251
	v_rcp_f32_e32 v244, v244
	v_rcp_f32_e32 v245, v245
	v_rcp_f32_e32 v246, v246
	v_rcp_f32_e32 v247, v247
	v_rcp_f32_e32 v248, v248
	v_rcp_f32_e32 v249, v249
	v_rcp_f32_e32 v250, v250
	v_rcp_f32_e32 v251, v251
	v_pk_mul_f32 v[236:237], v[236:237], v[244:245]
	v_pk_mul_f32 v[238:239], v[238:239], v[246:247]
	v_pk_mul_f32 v[240:241], v[240:241], v[248:249]
	v_pk_mul_f32 v[242:243], v[242:243], v[250:251]
	v_pk_mul_f32 v[236:237], v[4:5], v[236:237]
	v_pk_mul_f32 v[238:239], v[4:5], v[238:239]
	v_pk_mul_f32 v[240:241], v[4:5], v[240:241]
	v_pk_mul_f32 v[242:243], v[4:5], v[242:243]
	v_cvt_pk_bf16_f32 v224, v236, v237
	v_cvt_pk_bf16_f32 v225, v238, v239
	v_cvt_pk_bf16_f32 v226, v240, v241
	v_cvt_pk_bf16_f32 v227, v242, v243
	global_store_dwordx4 v8, v[224:227], s[30:31] offset:768
	s_waitcnt vmcnt(26)
	v_lshlrev_b32_e32 v244, 16, v130
	v_and_b32_e32 v245, 0xffff0000, v130
	v_lshlrev_b32_e32 v246, 16, v131
	v_and_b32_e32 v247, 0xffff0000, v131
	v_lshlrev_b32_e32 v248, 16, v132
	v_and_b32_e32 v249, 0xffff0000, v132
	v_lshlrev_b32_e32 v250, 16, v133
	v_and_b32_e32 v251, 0xffff0000, v133
	v_mul_f32_e32 v252, v244, v244
	v_fmac_f32_e32 v252, v245, v245
	v_fmac_f32_e32 v252, v246, v246
	v_fmac_f32_e32 v252, v247, v247
	v_fmac_f32_e32 v252, v248, v248
	v_fmac_f32_e32 v252, v249, v249
	v_fmac_f32_e32 v252, v250, v250
	v_fmac_f32_e32 v252, v251, v251
	s_nop 1
	v_add_f32_dpp v252, v252, v252 quad_perm:[1,0,3,2] row_mask:0xf bank_mask:0xf bound_ctrl:1
	s_nop 1
	v_add_f32_dpp v252, v252, v252 quad_perm:[2,3,0,1] row_mask:0xf bank_mask:0xf bound_ctrl:1
	s_nop 1
	v_add_f32_dpp v252, v252, v252 row_half_mirror row_mask:0xf bank_mask:0xf bound_ctrl:1
	s_nop 1
	v_add_f32_dpp v252, v252, v252 row_mirror row_mask:0xf bank_mask:0xf bound_ctrl:1
	v_lshlrev_b32_e32 v130, 16, v134
	v_and_b32_e32 v131, 0xffff0000, v134
	v_lshlrev_b32_e32 v132, 16, v135
	v_and_b32_e32 v133, 0xffff0000, v135
	v_lshlrev_b32_e32 v134, 16, v136
	v_and_b32_e32 v135, 0xffff0000, v136
	v_lshlrev_b32_e32 v136, 16, v137
	v_and_b32_e32 v137, 0xffff0000, v137
	s_nop 0
	v_readlane_b32 s40, v252, 0
	v_readlane_b32 s41, v252, 16
	v_readlane_b32 s42, v252, 32
	v_readlane_b32 s43, v252, 48
	v_readlane_b32 s44, v253, 48
	v_pk_fma_f32 v[236:237], v[106:107], v[18:19], v[10:11]
	v_pk_fma_f32 v[238:239], v[108:109], v[20:21], v[12:13]
	v_pk_fma_f32 v[240:241], v[110:111], v[22:23], v[14:15]
	v_pk_fma_f32 v[242:243], v[112:113], v[24:25], v[16:17]
	v_pk_fma_f32 v[236:237], v[114:115], v[26:27], v[236:237]
	v_pk_fma_f32 v[238:239], v[116:117], v[28:29], v[238:239]
	v_pk_fma_f32 v[240:241], v[118:119], v[30:31], v[240:241]
	v_pk_fma_f32 v[242:243], v[120:121], v[32:33], v[242:243]
	v_pk_fma_f32 v[236:237], v[122:123], v[34:35], v[236:237]
	v_pk_fma_f32 v[238:239], v[124:125], v[36:37], v[238:239]
	v_pk_fma_f32 v[240:241], v[126:127], v[38:39], v[240:241]
	v_pk_fma_f32 v[242:243], v[128:129], v[40:41], v[242:243]
	v_pk_fma_f32 v[236:237], v[130:131], v[42:43], v[236:237]
	v_pk_fma_f32 v[238:239], v[132:133], v[44:45], v[238:239]
	v_pk_fma_f32 v[240:241], v[134:135], v[46:47], v[240:241]
	v_pk_fma_f32 v[242:243], v[136:137], v[48:49], v[242:243]
	v_writelane_b32 v218, s40, 7
	v_writelane_b32 v219, s41, 7
	v_writelane_b32 v220, s42, 7
	v_writelane_b32 v221, s43, 7
	v_writelane_b32 v222, s44, 7
	v_mul_f32_e32 v244, 0xbfb8aa3b, v236
	v_mul_f32_e32 v245, 0xbfb8aa3b, v237
	v_mul_f32_e32 v246, 0xbfb8aa3b, v238
	v_mul_f32_e32 v247, 0xbfb8aa3b, v239
	v_mul_f32_e32 v248, 0xbfb8aa3b, v240
	v_mul_f32_e32 v249, 0xbfb8aa3b, v241
	v_mul_f32_e32 v250, 0xbfb8aa3b, v242
	v_mul_f32_e32 v251, 0xbfb8aa3b, v243
	v_exp_f32_e32 v244, v244
	v_exp_f32_e32 v245, v245
	v_exp_f32_e32 v246, v246
	v_exp_f32_e32 v247, v247
	v_exp_f32_e32 v248, v248
	v_exp_f32_e32 v249, v249
	v_exp_f32_e32 v250, v250
	v_exp_f32_e32 v251, v251
	v_add_f32_e32 v244, 1.0, v244
	v_add_f32_e32 v245, 1.0, v245
	v_add_f32_e32 v246, 1.0, v246
	v_add_f32_e32 v247, 1.0, v247
	v_add_f32_e32 v248, 1.0, v248
	v_add_f32_e32 v249, 1.0, v249
	v_add_f32_e32 v250, 1.0, v250
	v_add_f32_e32 v251, 1.0, v251
	v_rcp_f32_e32 v244, v244
	v_rcp_f32_e32 v245, v245
	v_rcp_f32_e32 v246, v246
	v_rcp_f32_e32 v247, v247
	v_rcp_f32_e32 v248, v248
	v_rcp_f32_e32 v249, v249
	v_rcp_f32_e32 v250, v250
	v_rcp_f32_e32 v251, v251
	v_pk_mul_f32 v[236:237], v[236:237], v[244:245]
	v_pk_mul_f32 v[238:239], v[238:239], v[246:247]
	v_pk_mul_f32 v[240:241], v[240:241], v[248:249]
	v_pk_mul_f32 v[242:243], v[242:243], v[250:251]
	v_pk_mul_f32 v[236:237], v[4:5], v[236:237]
	v_pk_mul_f32 v[238:239], v[4:5], v[238:239]
	v_pk_mul_f32 v[240:241], v[4:5], v[240:241]
	v_pk_mul_f32 v[242:243], v[4:5], v[242:243]
	v_cvt_pk_bf16_f32 v228, v236, v237
	v_cvt_pk_bf16_f32 v229, v238, v239
	v_cvt_pk_bf16_f32 v230, v240, v241
	v_cvt_pk_bf16_f32 v231, v242, v243
	global_store_dwordx4 v8, v[228:231], s[30:31] offset:896
	s_waitcnt vmcnt(24)
	v_lshlrev_b32_e32 v244, 16, v210
	v_and_b32_e32 v245, 0xffff0000, v210
	v_lshlrev_b32_e32 v246, 16, v211
	v_and_b32_e32 v247, 0xffff0000, v211
	v_lshlrev_b32_e32 v248, 16, v212
	v_and_b32_e32 v249, 0xffff0000, v212
	v_lshlrev_b32_e32 v250, 16, v213
	v_and_b32_e32 v251, 0xffff0000, v213
	v_mul_f32_e32 v253, v244, v244
	v_fmac_f32_e32 v253, v245, v245
	v_fmac_f32_e32 v253, v246, v246
	v_fmac_f32_e32 v253, v247, v247
	v_fmac_f32_e32 v253, v248, v248
	v_fmac_f32_e32 v253, v249, v249
	v_fmac_f32_e32 v253, v250, v250
	v_fmac_f32_e32 v253, v251, v251
	s_nop 1
	v_add_f32_dpp v253, v253, v253 quad_perm:[1,0,3,2] row_mask:0xf bank_mask:0xf bound_ctrl:1
	s_nop 1
	v_add_f32_dpp v253, v253, v253 quad_perm:[2,3,0,1] row_mask:0xf bank_mask:0xf bound_ctrl:1
	s_nop 1
	v_add_f32_dpp v253, v253, v253 row_half_mirror row_mask:0xf bank_mask:0xf bound_ctrl:1
	s_nop 1
	v_add_f32_dpp v253, v253, v253 row_mirror row_mask:0xf bank_mask:0xf bound_ctrl:1
	v_lshlrev_b32_e32 v244, 16, v138
	v_and_b32_e32 v245, 0xffff0000, v138
	v_lshlrev_b32_e32 v246, 16, v139
	v_and_b32_e32 v247, 0xffff0000, v139
	v_lshlrev_b32_e32 v248, 16, v140
	v_and_b32_e32 v249, 0xffff0000, v140
	v_lshlrev_b32_e32 v250, 16, v141
	v_and_b32_e32 v251, 0xffff0000, v141
	v_mul_f32_e32 v252, v244, v244
	v_fmac_f32_e32 v252, v245, v245
	v_fmac_f32_e32 v252, v246, v246
	v_fmac_f32_e32 v252, v247, v247
	v_fmac_f32_e32 v252, v248, v248
	v_fmac_f32_e32 v252, v249, v249
	v_fmac_f32_e32 v252, v250, v250
	v_fmac_f32_e32 v252, v251, v251
	s_nop 1
	v_add_f32_dpp v252, v252, v252 quad_perm:[1,0,3,2] row_mask:0xf bank_mask:0xf bound_ctrl:1
	s_nop 1
	v_add_f32_dpp v252, v252, v252 quad_perm:[2,3,0,1] row_mask:0xf bank_mask:0xf bound_ctrl:1
	s_nop 1
	v_add_f32_dpp v252, v252, v252 row_half_mirror row_mask:0xf bank_mask:0xf bound_ctrl:1
	s_nop 1
	v_add_f32_dpp v252, v252, v252 row_mirror row_mask:0xf bank_mask:0xf bound_ctrl:1
	v_lshlrev_b32_e32 v138, 16, v142
	v_and_b32_e32 v139, 0xffff0000, v142
	v_lshlrev_b32_e32 v140, 16, v143
	v_and_b32_e32 v141, 0xffff0000, v143
	v_lshlrev_b32_e32 v142, 16, v144
	v_and_b32_e32 v143, 0xffff0000, v144
	v_lshlrev_b32_e32 v144, 16, v145
	v_and_b32_e32 v145, 0xffff0000, v145
	s_nop 0
	v_readlane_b32 s40, v252, 0
	v_readlane_b32 s41, v252, 16
	v_readlane_b32 s42, v252, 32
	v_readlane_b32 s43, v252, 48
	v_readlane_b32 s44, v253, 0
	v_pk_fma_f32 v[236:237], v[114:115], v[18:19], v[10:11]
	v_pk_fma_f32 v[238:239], v[116:117], v[20:21], v[12:13]
	v_pk_fma_f32 v[240:241], v[118:119], v[22:23], v[14:15]
	v_pk_fma_f32 v[242:243], v[120:121], v[24:25], v[16:17]
	v_pk_fma_f32 v[236:237], v[122:123], v[26:27], v[236:237]
	v_pk_fma_f32 v[238:239], v[124:125], v[28:29], v[238:239]
	v_pk_fma_f32 v[240:241], v[126:127], v[30:31], v[240:241]
	v_pk_fma_f32 v[242:243], v[128:129], v[32:33], v[242:243]
	v_pk_fma_f32 v[236:237], v[130:131], v[34:35], v[236:237]
	v_pk_fma_f32 v[238:239], v[132:133], v[36:37], v[238:239]
	v_pk_fma_f32 v[240:241], v[134:135], v[38:39], v[240:241]
	v_pk_fma_f32 v[242:243], v[136:137], v[40:41], v[242:243]
	v_pk_fma_f32 v[236:237], v[138:139], v[42:43], v[236:237]
	v_pk_fma_f32 v[238:239], v[140:141], v[44:45], v[238:239]
	v_pk_fma_f32 v[240:241], v[142:143], v[46:47], v[240:241]
	v_pk_fma_f32 v[242:243], v[144:145], v[48:49], v[242:243]
	v_writelane_b32 v218, s40, 8
	v_writelane_b32 v219, s41, 8
	v_writelane_b32 v220, s42, 8
	v_writelane_b32 v221, s43, 8
	v_writelane_b32 v222, s44, 8
	v_mul_f32_e32 v244, 0xbfb8aa3b, v236
	v_mul_f32_e32 v245, 0xbfb8aa3b, v237
	v_mul_f32_e32 v246, 0xbfb8aa3b, v238
	v_mul_f32_e32 v247, 0xbfb8aa3b, v239
	v_mul_f32_e32 v248, 0xbfb8aa3b, v240
	v_mul_f32_e32 v249, 0xbfb8aa3b, v241
	v_mul_f32_e32 v250, 0xbfb8aa3b, v242
	v_mul_f32_e32 v251, 0xbfb8aa3b, v243
	v_exp_f32_e32 v244, v244
	v_exp_f32_e32 v245, v245
	v_exp_f32_e32 v246, v246
	v_exp_f32_e32 v247, v247
	v_exp_f32_e32 v248, v248
	v_exp_f32_e32 v249, v249
	v_exp_f32_e32 v250, v250
	v_exp_f32_e32 v251, v251
	v_add_f32_e32 v244, 1.0, v244
	v_add_f32_e32 v245, 1.0, v245
	v_add_f32_e32 v246, 1.0, v246
	v_add_f32_e32 v247, 1.0, v247
	v_add_f32_e32 v248, 1.0, v248
	v_add_f32_e32 v249, 1.0, v249
	v_add_f32_e32 v250, 1.0, v250
	v_add_f32_e32 v251, 1.0, v251
	v_rcp_f32_e32 v244, v244
	v_rcp_f32_e32 v245, v245
	v_rcp_f32_e32 v246, v246
	v_rcp_f32_e32 v247, v247
	v_rcp_f32_e32 v248, v248
	v_rcp_f32_e32 v249, v249
	v_rcp_f32_e32 v250, v250
	v_rcp_f32_e32 v251, v251
	v_pk_mul_f32 v[236:237], v[236:237], v[244:245]
	v_pk_mul_f32 v[238:239], v[238:239], v[246:247]
	v_pk_mul_f32 v[240:241], v[240:241], v[248:249]
	v_pk_mul_f32 v[242:243], v[242:243], v[250:251]
	v_pk_mul_f32 v[236:237], v[4:5], v[236:237]
	v_pk_mul_f32 v[238:239], v[4:5], v[238:239]
	v_pk_mul_f32 v[240:241], v[4:5], v[240:241]
	v_pk_mul_f32 v[242:243], v[4:5], v[242:243]
	v_cvt_pk_bf16_f32 v224, v236, v237
	v_cvt_pk_bf16_f32 v225, v238, v239
	v_cvt_pk_bf16_f32 v226, v240, v241
	v_cvt_pk_bf16_f32 v227, v242, v243
	global_store_dwordx4 v8, v[224:227], s[30:31] offset:1024
	s_waitcnt vmcnt(23)
	v_lshlrev_b32_e32 v244, 16, v146
	v_and_b32_e32 v245, 0xffff0000, v146
	v_lshlrev_b32_e32 v246, 16, v147
	v_and_b32_e32 v247, 0xffff0000, v147
	v_lshlrev_b32_e32 v248, 16, v148
	v_and_b32_e32 v249, 0xffff0000, v148
	v_lshlrev_b32_e32 v250, 16, v149
	v_and_b32_e32 v251, 0xffff0000, v149
	v_mul_f32_e32 v252, v244, v244
	v_fmac_f32_e32 v252, v245, v245
	v_fmac_f32_e32 v252, v246, v246
	v_fmac_f32_e32 v252, v247, v247
	v_fmac_f32_e32 v252, v248, v248
	v_fmac_f32_e32 v252, v249, v249
	v_fmac_f32_e32 v252, v250, v250
	v_fmac_f32_e32 v252, v251, v251
	s_nop 1
	v_add_f32_dpp v252, v252, v252 quad_perm:[1,0,3,2] row_mask:0xf bank_mask:0xf bound_ctrl:1
	s_nop 1
	v_add_f32_dpp v252, v252, v252 quad_perm:[2,3,0,1] row_mask:0xf bank_mask:0xf bound_ctrl:1
	s_nop 1
	v_add_f32_dpp v252, v252, v252 row_half_mirror row_mask:0xf bank_mask:0xf bound_ctrl:1
	s_nop 1
	v_add_f32_dpp v252, v252, v252 row_mirror row_mask:0xf bank_mask:0xf bound_ctrl:1
	v_lshlrev_b32_e32 v146, 16, v150
	v_and_b32_e32 v147, 0xffff0000, v150
	v_lshlrev_b32_e32 v148, 16, v151
	v_and_b32_e32 v149, 0xffff0000, v151
	v_lshlrev_b32_e32 v150, 16, v152
	v_and_b32_e32 v151, 0xffff0000, v152
	v_lshlrev_b32_e32 v152, 16, v153
	v_and_b32_e32 v153, 0xffff0000, v153
	s_nop 0
	v_readlane_b32 s40, v252, 0
	v_readlane_b32 s41, v252, 16
	v_readlane_b32 s42, v252, 32
	v_readlane_b32 s43, v252, 48
	v_readlane_b32 s44, v253, 16
	v_pk_fma_f32 v[236:237], v[122:123], v[18:19], v[10:11]
	v_pk_fma_f32 v[238:239], v[124:125], v[20:21], v[12:13]
	v_pk_fma_f32 v[240:241], v[126:127], v[22:23], v[14:15]
	v_pk_fma_f32 v[242:243], v[128:129], v[24:25], v[16:17]
	v_pk_fma_f32 v[236:237], v[130:131], v[26:27], v[236:237]
	v_pk_fma_f32 v[238:239], v[132:133], v[28:29], v[238:239]
	v_pk_fma_f32 v[240:241], v[134:135], v[30:31], v[240:241]
	v_pk_fma_f32 v[242:243], v[136:137], v[32:33], v[242:243]
	v_pk_fma_f32 v[236:237], v[138:139], v[34:35], v[236:237]
	v_pk_fma_f32 v[238:239], v[140:141], v[36:37], v[238:239]
	v_pk_fma_f32 v[240:241], v[142:143], v[38:39], v[240:241]
	v_pk_fma_f32 v[242:243], v[144:145], v[40:41], v[242:243]
	v_pk_fma_f32 v[236:237], v[146:147], v[42:43], v[236:237]
	v_pk_fma_f32 v[238:239], v[148:149], v[44:45], v[238:239]
	v_pk_fma_f32 v[240:241], v[150:151], v[46:47], v[240:241]
	v_pk_fma_f32 v[242:243], v[152:153], v[48:49], v[242:243]
	v_writelane_b32 v218, s40, 9
	v_writelane_b32 v219, s41, 9
	v_writelane_b32 v220, s42, 9
	v_writelane_b32 v221, s43, 9
	v_writelane_b32 v222, s44, 9
	v_mul_f32_e32 v244, 0xbfb8aa3b, v236
	v_mul_f32_e32 v245, 0xbfb8aa3b, v237
	v_mul_f32_e32 v246, 0xbfb8aa3b, v238
	v_mul_f32_e32 v247, 0xbfb8aa3b, v239
	v_mul_f32_e32 v248, 0xbfb8aa3b, v240
	v_mul_f32_e32 v249, 0xbfb8aa3b, v241
	v_mul_f32_e32 v250, 0xbfb8aa3b, v242
	v_mul_f32_e32 v251, 0xbfb8aa3b, v243
	v_exp_f32_e32 v244, v244
	v_exp_f32_e32 v245, v245
	v_exp_f32_e32 v246, v246
	v_exp_f32_e32 v247, v247
	v_exp_f32_e32 v248, v248
	v_exp_f32_e32 v249, v249
	v_exp_f32_e32 v250, v250
	v_exp_f32_e32 v251, v251
	v_add_f32_e32 v244, 1.0, v244
	v_add_f32_e32 v245, 1.0, v245
	v_add_f32_e32 v246, 1.0, v246
	v_add_f32_e32 v247, 1.0, v247
	v_add_f32_e32 v248, 1.0, v248
	v_add_f32_e32 v249, 1.0, v249
	v_add_f32_e32 v250, 1.0, v250
	v_add_f32_e32 v251, 1.0, v251
	v_rcp_f32_e32 v244, v244
	v_rcp_f32_e32 v245, v245
	v_rcp_f32_e32 v246, v246
	v_rcp_f32_e32 v247, v247
	v_rcp_f32_e32 v248, v248
	v_rcp_f32_e32 v249, v249
	v_rcp_f32_e32 v250, v250
	v_rcp_f32_e32 v251, v251
	v_pk_mul_f32 v[236:237], v[236:237], v[244:245]
	v_pk_mul_f32 v[238:239], v[238:239], v[246:247]
	v_pk_mul_f32 v[240:241], v[240:241], v[248:249]
	v_pk_mul_f32 v[242:243], v[242:243], v[250:251]
	v_pk_mul_f32 v[236:237], v[4:5], v[236:237]
	v_pk_mul_f32 v[238:239], v[4:5], v[238:239]
	v_pk_mul_f32 v[240:241], v[4:5], v[240:241]
	v_pk_mul_f32 v[242:243], v[4:5], v[242:243]
	v_cvt_pk_bf16_f32 v228, v236, v237
	v_cvt_pk_bf16_f32 v229, v238, v239
	v_cvt_pk_bf16_f32 v230, v240, v241
	v_cvt_pk_bf16_f32 v231, v242, v243
	global_store_dwordx4 v8, v[228:231], s[30:31] offset:1152
	s_waitcnt vmcnt(22)
	v_lshlrev_b32_e32 v244, 16, v154
	v_and_b32_e32 v245, 0xffff0000, v154
	v_lshlrev_b32_e32 v246, 16, v155
	v_and_b32_e32 v247, 0xffff0000, v155
	v_lshlrev_b32_e32 v248, 16, v156
	v_and_b32_e32 v249, 0xffff0000, v156
	v_lshlrev_b32_e32 v250, 16, v157
	v_and_b32_e32 v251, 0xffff0000, v157
	v_mul_f32_e32 v252, v244, v244
	v_fmac_f32_e32 v252, v245, v245
	v_fmac_f32_e32 v252, v246, v246
	v_fmac_f32_e32 v252, v247, v247
	v_fmac_f32_e32 v252, v248, v248
	v_fmac_f32_e32 v252, v249, v249
	v_fmac_f32_e32 v252, v250, v250
	v_fmac_f32_e32 v252, v251, v251
	s_nop 1
	v_add_f32_dpp v252, v252, v252 quad_perm:[1,0,3,2] row_mask:0xf bank_mask:0xf bound_ctrl:1
	s_nop 1
	v_add_f32_dpp v252, v252, v252 quad_perm:[2,3,0,1] row_mask:0xf bank_mask:0xf bound_ctrl:1
	s_nop 1
	v_add_f32_dpp v252, v252, v252 row_half_mirror row_mask:0xf bank_mask:0xf bound_ctrl:1
	s_nop 1
	v_add_f32_dpp v252, v252, v252 row_mirror row_mask:0xf bank_mask:0xf bound_ctrl:1
	v_lshlrev_b32_e32 v154, 16, v158
	v_and_b32_e32 v155, 0xffff0000, v158
	v_lshlrev_b32_e32 v156, 16, v159
	v_and_b32_e32 v157, 0xffff0000, v159
	v_lshlrev_b32_e32 v158, 16, v160
	v_and_b32_e32 v159, 0xffff0000, v160
	v_lshlrev_b32_e32 v160, 16, v161
	v_and_b32_e32 v161, 0xffff0000, v161
	s_nop 0
	v_readlane_b32 s40, v252, 0
	v_readlane_b32 s41, v252, 16
	v_readlane_b32 s42, v252, 32
	v_readlane_b32 s43, v252, 48
	v_readlane_b32 s44, v253, 32
	v_pk_fma_f32 v[236:237], v[130:131], v[18:19], v[10:11]
	v_pk_fma_f32 v[238:239], v[132:133], v[20:21], v[12:13]
	v_pk_fma_f32 v[240:241], v[134:135], v[22:23], v[14:15]
	v_pk_fma_f32 v[242:243], v[136:137], v[24:25], v[16:17]
	v_pk_fma_f32 v[236:237], v[138:139], v[26:27], v[236:237]
	v_pk_fma_f32 v[238:239], v[140:141], v[28:29], v[238:239]
	v_pk_fma_f32 v[240:241], v[142:143], v[30:31], v[240:241]
	v_pk_fma_f32 v[242:243], v[144:145], v[32:33], v[242:243]
	v_pk_fma_f32 v[236:237], v[146:147], v[34:35], v[236:237]
	v_pk_fma_f32 v[238:239], v[148:149], v[36:37], v[238:239]
	v_pk_fma_f32 v[240:241], v[150:151], v[38:39], v[240:241]
	v_pk_fma_f32 v[242:243], v[152:153], v[40:41], v[242:243]
	v_pk_fma_f32 v[236:237], v[154:155], v[42:43], v[236:237]
	v_pk_fma_f32 v[238:239], v[156:157], v[44:45], v[238:239]
	v_pk_fma_f32 v[240:241], v[158:159], v[46:47], v[240:241]
	v_pk_fma_f32 v[242:243], v[160:161], v[48:49], v[242:243]
	v_writelane_b32 v218, s40, 10
	v_writelane_b32 v219, s41, 10
	v_writelane_b32 v220, s42, 10
	v_writelane_b32 v221, s43, 10
	v_writelane_b32 v222, s44, 10
	v_mul_f32_e32 v244, 0xbfb8aa3b, v236
	v_mul_f32_e32 v245, 0xbfb8aa3b, v237
	v_mul_f32_e32 v246, 0xbfb8aa3b, v238
	v_mul_f32_e32 v247, 0xbfb8aa3b, v239
	v_mul_f32_e32 v248, 0xbfb8aa3b, v240
	v_mul_f32_e32 v249, 0xbfb8aa3b, v241
	v_mul_f32_e32 v250, 0xbfb8aa3b, v242
	v_mul_f32_e32 v251, 0xbfb8aa3b, v243
	v_exp_f32_e32 v244, v244
	v_exp_f32_e32 v245, v245
	v_exp_f32_e32 v246, v246
	v_exp_f32_e32 v247, v247
	v_exp_f32_e32 v248, v248
	v_exp_f32_e32 v249, v249
	v_exp_f32_e32 v250, v250
	v_exp_f32_e32 v251, v251
	v_add_f32_e32 v244, 1.0, v244
	v_add_f32_e32 v245, 1.0, v245
	v_add_f32_e32 v246, 1.0, v246
	v_add_f32_e32 v247, 1.0, v247
	v_add_f32_e32 v248, 1.0, v248
	v_add_f32_e32 v249, 1.0, v249
	v_add_f32_e32 v250, 1.0, v250
	v_add_f32_e32 v251, 1.0, v251
	v_rcp_f32_e32 v244, v244
	v_rcp_f32_e32 v245, v245
	v_rcp_f32_e32 v246, v246
	v_rcp_f32_e32 v247, v247
	v_rcp_f32_e32 v248, v248
	v_rcp_f32_e32 v249, v249
	v_rcp_f32_e32 v250, v250
	v_rcp_f32_e32 v251, v251
	v_pk_mul_f32 v[236:237], v[236:237], v[244:245]
	v_pk_mul_f32 v[238:239], v[238:239], v[246:247]
	v_pk_mul_f32 v[240:241], v[240:241], v[248:249]
	v_pk_mul_f32 v[242:243], v[242:243], v[250:251]
	v_pk_mul_f32 v[236:237], v[4:5], v[236:237]
	v_pk_mul_f32 v[238:239], v[4:5], v[238:239]
	v_pk_mul_f32 v[240:241], v[4:5], v[240:241]
	v_pk_mul_f32 v[242:243], v[4:5], v[242:243]
	v_cvt_pk_bf16_f32 v224, v236, v237
	v_cvt_pk_bf16_f32 v225, v238, v239
	v_cvt_pk_bf16_f32 v226, v240, v241
	v_cvt_pk_bf16_f32 v227, v242, v243
	global_store_dwordx4 v8, v[224:227], s[30:31] offset:1280
	s_waitcnt vmcnt(21)
	v_lshlrev_b32_e32 v244, 16, v162
	v_and_b32_e32 v245, 0xffff0000, v162
	v_lshlrev_b32_e32 v246, 16, v163
	v_and_b32_e32 v247, 0xffff0000, v163
	v_lshlrev_b32_e32 v248, 16, v164
	v_and_b32_e32 v249, 0xffff0000, v164
	v_lshlrev_b32_e32 v250, 16, v165
	v_and_b32_e32 v251, 0xffff0000, v165
	v_mul_f32_e32 v252, v244, v244
	v_fmac_f32_e32 v252, v245, v245
	v_fmac_f32_e32 v252, v246, v246
	v_fmac_f32_e32 v252, v247, v247
	v_fmac_f32_e32 v252, v248, v248
	v_fmac_f32_e32 v252, v249, v249
	v_fmac_f32_e32 v252, v250, v250
	v_fmac_f32_e32 v252, v251, v251
	s_nop 1
	v_add_f32_dpp v252, v252, v252 quad_perm:[1,0,3,2] row_mask:0xf bank_mask:0xf bound_ctrl:1
	s_nop 1
	v_add_f32_dpp v252, v252, v252 quad_perm:[2,3,0,1] row_mask:0xf bank_mask:0xf bound_ctrl:1
	s_nop 1
	v_add_f32_dpp v252, v252, v252 row_half_mirror row_mask:0xf bank_mask:0xf bound_ctrl:1
	s_nop 1
	v_add_f32_dpp v252, v252, v252 row_mirror row_mask:0xf bank_mask:0xf bound_ctrl:1
	v_lshlrev_b32_e32 v162, 16, v166
	v_and_b32_e32 v163, 0xffff0000, v166
	v_lshlrev_b32_e32 v164, 16, v167
	v_and_b32_e32 v165, 0xffff0000, v167
	v_lshlrev_b32_e32 v166, 16, v168
	v_and_b32_e32 v167, 0xffff0000, v168
	v_lshlrev_b32_e32 v168, 16, v169
	v_and_b32_e32 v169, 0xffff0000, v169
	s_nop 0
	v_readlane_b32 s40, v252, 0
	v_readlane_b32 s41, v252, 16
	v_readlane_b32 s42, v252, 32
	v_readlane_b32 s43, v252, 48
	v_readlane_b32 s44, v253, 48
	v_pk_fma_f32 v[236:237], v[138:139], v[18:19], v[10:11]
	v_pk_fma_f32 v[238:239], v[140:141], v[20:21], v[12:13]
	v_pk_fma_f32 v[240:241], v[142:143], v[22:23], v[14:15]
	v_pk_fma_f32 v[242:243], v[144:145], v[24:25], v[16:17]
	v_pk_fma_f32 v[236:237], v[146:147], v[26:27], v[236:237]
	v_pk_fma_f32 v[238:239], v[148:149], v[28:29], v[238:239]
	v_pk_fma_f32 v[240:241], v[150:151], v[30:31], v[240:241]
	v_pk_fma_f32 v[242:243], v[152:153], v[32:33], v[242:243]
	v_pk_fma_f32 v[236:237], v[154:155], v[34:35], v[236:237]
	v_pk_fma_f32 v[238:239], v[156:157], v[36:37], v[238:239]
	v_pk_fma_f32 v[240:241], v[158:159], v[38:39], v[240:241]
	v_pk_fma_f32 v[242:243], v[160:161], v[40:41], v[242:243]
	v_pk_fma_f32 v[236:237], v[162:163], v[42:43], v[236:237]
	v_pk_fma_f32 v[238:239], v[164:165], v[44:45], v[238:239]
	v_pk_fma_f32 v[240:241], v[166:167], v[46:47], v[240:241]
	v_pk_fma_f32 v[242:243], v[168:169], v[48:49], v[242:243]
	v_writelane_b32 v218, s40, 11
	v_writelane_b32 v219, s41, 11
	v_writelane_b32 v220, s42, 11
	v_writelane_b32 v221, s43, 11
	v_writelane_b32 v222, s44, 11
	v_mul_f32_e32 v244, 0xbfb8aa3b, v236
	v_mul_f32_e32 v245, 0xbfb8aa3b, v237
	v_mul_f32_e32 v246, 0xbfb8aa3b, v238
	v_mul_f32_e32 v247, 0xbfb8aa3b, v239
	v_mul_f32_e32 v248, 0xbfb8aa3b, v240
	v_mul_f32_e32 v249, 0xbfb8aa3b, v241
	v_mul_f32_e32 v250, 0xbfb8aa3b, v242
	v_mul_f32_e32 v251, 0xbfb8aa3b, v243
	v_exp_f32_e32 v244, v244
	v_exp_f32_e32 v245, v245
	v_exp_f32_e32 v246, v246
	v_exp_f32_e32 v247, v247
	v_exp_f32_e32 v248, v248
	v_exp_f32_e32 v249, v249
	v_exp_f32_e32 v250, v250
	v_exp_f32_e32 v251, v251
	v_add_f32_e32 v244, 1.0, v244
	v_add_f32_e32 v245, 1.0, v245
	v_add_f32_e32 v246, 1.0, v246
	v_add_f32_e32 v247, 1.0, v247
	v_add_f32_e32 v248, 1.0, v248
	v_add_f32_e32 v249, 1.0, v249
	v_add_f32_e32 v250, 1.0, v250
	v_add_f32_e32 v251, 1.0, v251
	v_rcp_f32_e32 v244, v244
	v_rcp_f32_e32 v245, v245
	v_rcp_f32_e32 v246, v246
	v_rcp_f32_e32 v247, v247
	v_rcp_f32_e32 v248, v248
	v_rcp_f32_e32 v249, v249
	v_rcp_f32_e32 v250, v250
	v_rcp_f32_e32 v251, v251
	v_pk_mul_f32 v[236:237], v[236:237], v[244:245]
	v_pk_mul_f32 v[238:239], v[238:239], v[246:247]
	v_pk_mul_f32 v[240:241], v[240:241], v[248:249]
	v_pk_mul_f32 v[242:243], v[242:243], v[250:251]
	v_pk_mul_f32 v[236:237], v[4:5], v[236:237]
	v_pk_mul_f32 v[238:239], v[4:5], v[238:239]
	v_pk_mul_f32 v[240:241], v[4:5], v[240:241]
	v_pk_mul_f32 v[242:243], v[4:5], v[242:243]
	v_cvt_pk_bf16_f32 v228, v236, v237
	v_cvt_pk_bf16_f32 v229, v238, v239
	v_cvt_pk_bf16_f32 v230, v240, v241
	v_cvt_pk_bf16_f32 v231, v242, v243
	global_store_dwordx4 v8, v[228:231], s[30:31] offset:1408
	s_waitcnt vmcnt(19)
	v_lshlrev_b32_e32 v244, 16, v214
	v_and_b32_e32 v245, 0xffff0000, v214
	v_lshlrev_b32_e32 v246, 16, v215
	v_and_b32_e32 v247, 0xffff0000, v215
	v_lshlrev_b32_e32 v248, 16, v216
	v_and_b32_e32 v249, 0xffff0000, v216
	v_lshlrev_b32_e32 v250, 16, v217
	v_and_b32_e32 v251, 0xffff0000, v217
	v_mul_f32_e32 v253, v244, v244
	v_fmac_f32_e32 v253, v245, v245
	v_fmac_f32_e32 v253, v246, v246
	v_fmac_f32_e32 v253, v247, v247
	v_fmac_f32_e32 v253, v248, v248
	v_fmac_f32_e32 v253, v249, v249
	v_fmac_f32_e32 v253, v250, v250
	v_fmac_f32_e32 v253, v251, v251
	s_nop 1
	v_add_f32_dpp v253, v253, v253 quad_perm:[1,0,3,2] row_mask:0xf bank_mask:0xf bound_ctrl:1
	s_nop 1
	v_add_f32_dpp v253, v253, v253 quad_perm:[2,3,0,1] row_mask:0xf bank_mask:0xf bound_ctrl:1
	s_nop 1
	v_add_f32_dpp v253, v253, v253 row_half_mirror row_mask:0xf bank_mask:0xf bound_ctrl:1
	s_nop 1
	v_add_f32_dpp v253, v253, v253 row_mirror row_mask:0xf bank_mask:0xf bound_ctrl:1
	v_lshlrev_b32_e32 v244, 16, v170
	v_and_b32_e32 v245, 0xffff0000, v170
	v_lshlrev_b32_e32 v246, 16, v171
	v_and_b32_e32 v247, 0xffff0000, v171
	v_lshlrev_b32_e32 v248, 16, v172
	v_and_b32_e32 v249, 0xffff0000, v172
	v_lshlrev_b32_e32 v250, 16, v173
	v_and_b32_e32 v251, 0xffff0000, v173
	v_mul_f32_e32 v252, v244, v244
	v_fmac_f32_e32 v252, v245, v245
	v_fmac_f32_e32 v252, v246, v246
	v_fmac_f32_e32 v252, v247, v247
	v_fmac_f32_e32 v252, v248, v248
	v_fmac_f32_e32 v252, v249, v249
	v_fmac_f32_e32 v252, v250, v250
	v_fmac_f32_e32 v252, v251, v251
	s_nop 1
	v_add_f32_dpp v252, v252, v252 quad_perm:[1,0,3,2] row_mask:0xf bank_mask:0xf bound_ctrl:1
	s_nop 1
	v_add_f32_dpp v252, v252, v252 quad_perm:[2,3,0,1] row_mask:0xf bank_mask:0xf bound_ctrl:1
	s_nop 1
	v_add_f32_dpp v252, v252, v252 row_half_mirror row_mask:0xf bank_mask:0xf bound_ctrl:1
	s_nop 1
	v_add_f32_dpp v252, v252, v252 row_mirror row_mask:0xf bank_mask:0xf bound_ctrl:1
	v_lshlrev_b32_e32 v170, 16, v174
	v_and_b32_e32 v171, 0xffff0000, v174
	v_lshlrev_b32_e32 v172, 16, v175
	v_and_b32_e32 v173, 0xffff0000, v175
	v_lshlrev_b32_e32 v174, 16, v176
	v_and_b32_e32 v175, 0xffff0000, v176
	v_lshlrev_b32_e32 v176, 16, v177
	v_and_b32_e32 v177, 0xffff0000, v177
	s_nop 0
	v_readlane_b32 s40, v252, 0
	v_readlane_b32 s41, v252, 16
	v_readlane_b32 s42, v252, 32
	v_readlane_b32 s43, v252, 48
	v_readlane_b32 s44, v253, 0
	v_pk_fma_f32 v[236:237], v[146:147], v[18:19], v[10:11]
	v_pk_fma_f32 v[238:239], v[148:149], v[20:21], v[12:13]
	v_pk_fma_f32 v[240:241], v[150:151], v[22:23], v[14:15]
	v_pk_fma_f32 v[242:243], v[152:153], v[24:25], v[16:17]
	v_pk_fma_f32 v[236:237], v[154:155], v[26:27], v[236:237]
	v_pk_fma_f32 v[238:239], v[156:157], v[28:29], v[238:239]
	v_pk_fma_f32 v[240:241], v[158:159], v[30:31], v[240:241]
	v_pk_fma_f32 v[242:243], v[160:161], v[32:33], v[242:243]
	v_pk_fma_f32 v[236:237], v[162:163], v[34:35], v[236:237]
	v_pk_fma_f32 v[238:239], v[164:165], v[36:37], v[238:239]
	v_pk_fma_f32 v[240:241], v[166:167], v[38:39], v[240:241]
	v_pk_fma_f32 v[242:243], v[168:169], v[40:41], v[242:243]
	v_pk_fma_f32 v[236:237], v[170:171], v[42:43], v[236:237]
	v_pk_fma_f32 v[238:239], v[172:173], v[44:45], v[238:239]
	v_pk_fma_f32 v[240:241], v[174:175], v[46:47], v[240:241]
	v_pk_fma_f32 v[242:243], v[176:177], v[48:49], v[242:243]
	v_writelane_b32 v218, s40, 12
	v_writelane_b32 v219, s41, 12
	v_writelane_b32 v220, s42, 12
	v_writelane_b32 v221, s43, 12
	v_writelane_b32 v222, s44, 12
	v_mul_f32_e32 v244, 0xbfb8aa3b, v236
	v_mul_f32_e32 v245, 0xbfb8aa3b, v237
	v_mul_f32_e32 v246, 0xbfb8aa3b, v238
	v_mul_f32_e32 v247, 0xbfb8aa3b, v239
	v_mul_f32_e32 v248, 0xbfb8aa3b, v240
	v_mul_f32_e32 v249, 0xbfb8aa3b, v241
	v_mul_f32_e32 v250, 0xbfb8aa3b, v242
	v_mul_f32_e32 v251, 0xbfb8aa3b, v243
	v_exp_f32_e32 v244, v244
	v_exp_f32_e32 v245, v245
	v_exp_f32_e32 v246, v246
	v_exp_f32_e32 v247, v247
	v_exp_f32_e32 v248, v248
	v_exp_f32_e32 v249, v249
	v_exp_f32_e32 v250, v250
	v_exp_f32_e32 v251, v251
	v_add_f32_e32 v244, 1.0, v244
	v_add_f32_e32 v245, 1.0, v245
	v_add_f32_e32 v246, 1.0, v246
	v_add_f32_e32 v247, 1.0, v247
	v_add_f32_e32 v248, 1.0, v248
	v_add_f32_e32 v249, 1.0, v249
	v_add_f32_e32 v250, 1.0, v250
	v_add_f32_e32 v251, 1.0, v251
	v_rcp_f32_e32 v244, v244
	v_rcp_f32_e32 v245, v245
	v_rcp_f32_e32 v246, v246
	v_rcp_f32_e32 v247, v247
	v_rcp_f32_e32 v248, v248
	v_rcp_f32_e32 v249, v249
	v_rcp_f32_e32 v250, v250
	v_rcp_f32_e32 v251, v251
	v_pk_mul_f32 v[236:237], v[236:237], v[244:245]
	v_pk_mul_f32 v[238:239], v[238:239], v[246:247]
	v_pk_mul_f32 v[240:241], v[240:241], v[248:249]
	v_pk_mul_f32 v[242:243], v[242:243], v[250:251]
	v_pk_mul_f32 v[236:237], v[4:5], v[236:237]
	v_pk_mul_f32 v[238:239], v[4:5], v[238:239]
	v_pk_mul_f32 v[240:241], v[4:5], v[240:241]
	v_pk_mul_f32 v[242:243], v[4:5], v[242:243]
	v_cvt_pk_bf16_f32 v224, v236, v237
	v_cvt_pk_bf16_f32 v225, v238, v239
	v_cvt_pk_bf16_f32 v226, v240, v241
	v_cvt_pk_bf16_f32 v227, v242, v243
	global_store_dwordx4 v8, v[224:227], s[30:31] offset:1536
	s_waitcnt vmcnt(18)
	v_lshlrev_b32_e32 v244, 16, v178
	v_and_b32_e32 v245, 0xffff0000, v178
	v_lshlrev_b32_e32 v246, 16, v179
	v_and_b32_e32 v247, 0xffff0000, v179
	v_lshlrev_b32_e32 v248, 16, v180
	v_and_b32_e32 v249, 0xffff0000, v180
	v_lshlrev_b32_e32 v250, 16, v181
	v_and_b32_e32 v251, 0xffff0000, v181
	v_mul_f32_e32 v252, v244, v244
	v_fmac_f32_e32 v252, v245, v245
	v_fmac_f32_e32 v252, v246, v246
	v_fmac_f32_e32 v252, v247, v247
	v_fmac_f32_e32 v252, v248, v248
	v_fmac_f32_e32 v252, v249, v249
	v_fmac_f32_e32 v252, v250, v250
	v_fmac_f32_e32 v252, v251, v251
	s_nop 1
	v_add_f32_dpp v252, v252, v252 quad_perm:[1,0,3,2] row_mask:0xf bank_mask:0xf bound_ctrl:1
	s_nop 1
	v_add_f32_dpp v252, v252, v252 quad_perm:[2,3,0,1] row_mask:0xf bank_mask:0xf bound_ctrl:1
	s_nop 1
	v_add_f32_dpp v252, v252, v252 row_half_mirror row_mask:0xf bank_mask:0xf bound_ctrl:1
	s_nop 1
	v_add_f32_dpp v252, v252, v252 row_mirror row_mask:0xf bank_mask:0xf bound_ctrl:1
	v_lshlrev_b32_e32 v178, 16, v182
	v_and_b32_e32 v179, 0xffff0000, v182
	v_lshlrev_b32_e32 v180, 16, v183
	v_and_b32_e32 v181, 0xffff0000, v183
	v_lshlrev_b32_e32 v182, 16, v184
	v_and_b32_e32 v183, 0xffff0000, v184
	v_lshlrev_b32_e32 v184, 16, v185
	v_and_b32_e32 v185, 0xffff0000, v185
	s_nop 0
	v_readlane_b32 s40, v252, 0
	v_readlane_b32 s41, v252, 16
	v_readlane_b32 s42, v252, 32
	v_readlane_b32 s43, v252, 48
	v_readlane_b32 s44, v253, 16
	v_pk_fma_f32 v[236:237], v[154:155], v[18:19], v[10:11]
	v_pk_fma_f32 v[238:239], v[156:157], v[20:21], v[12:13]
	v_pk_fma_f32 v[240:241], v[158:159], v[22:23], v[14:15]
	v_pk_fma_f32 v[242:243], v[160:161], v[24:25], v[16:17]
	v_pk_fma_f32 v[236:237], v[162:163], v[26:27], v[236:237]
	v_pk_fma_f32 v[238:239], v[164:165], v[28:29], v[238:239]
	v_pk_fma_f32 v[240:241], v[166:167], v[30:31], v[240:241]
	v_pk_fma_f32 v[242:243], v[168:169], v[32:33], v[242:243]
	v_pk_fma_f32 v[236:237], v[170:171], v[34:35], v[236:237]
	v_pk_fma_f32 v[238:239], v[172:173], v[36:37], v[238:239]
	v_pk_fma_f32 v[240:241], v[174:175], v[38:39], v[240:241]
	v_pk_fma_f32 v[242:243], v[176:177], v[40:41], v[242:243]
	v_pk_fma_f32 v[236:237], v[178:179], v[42:43], v[236:237]
	v_pk_fma_f32 v[238:239], v[180:181], v[44:45], v[238:239]
	v_pk_fma_f32 v[240:241], v[182:183], v[46:47], v[240:241]
	v_pk_fma_f32 v[242:243], v[184:185], v[48:49], v[242:243]
	v_writelane_b32 v218, s40, 13
	v_writelane_b32 v219, s41, 13
	v_writelane_b32 v220, s42, 13
	v_writelane_b32 v221, s43, 13
	v_writelane_b32 v222, s44, 13
	v_mul_f32_e32 v244, 0xbfb8aa3b, v236
	v_mul_f32_e32 v245, 0xbfb8aa3b, v237
	v_mul_f32_e32 v246, 0xbfb8aa3b, v238
	v_mul_f32_e32 v247, 0xbfb8aa3b, v239
	v_mul_f32_e32 v248, 0xbfb8aa3b, v240
	v_mul_f32_e32 v249, 0xbfb8aa3b, v241
	v_mul_f32_e32 v250, 0xbfb8aa3b, v242
	v_mul_f32_e32 v251, 0xbfb8aa3b, v243
	v_exp_f32_e32 v244, v244
	v_exp_f32_e32 v245, v245
	v_exp_f32_e32 v246, v246
	v_exp_f32_e32 v247, v247
	v_exp_f32_e32 v248, v248
	v_exp_f32_e32 v249, v249
	v_exp_f32_e32 v250, v250
	v_exp_f32_e32 v251, v251
	v_add_f32_e32 v244, 1.0, v244
	v_add_f32_e32 v245, 1.0, v245
	v_add_f32_e32 v246, 1.0, v246
	v_add_f32_e32 v247, 1.0, v247
	v_add_f32_e32 v248, 1.0, v248
	v_add_f32_e32 v249, 1.0, v249
	v_add_f32_e32 v250, 1.0, v250
	v_add_f32_e32 v251, 1.0, v251
	v_rcp_f32_e32 v244, v244
	v_rcp_f32_e32 v245, v245
	v_rcp_f32_e32 v246, v246
	v_rcp_f32_e32 v247, v247
	v_rcp_f32_e32 v248, v248
	v_rcp_f32_e32 v249, v249
	v_rcp_f32_e32 v250, v250
	v_rcp_f32_e32 v251, v251
	v_pk_mul_f32 v[236:237], v[236:237], v[244:245]
	v_pk_mul_f32 v[238:239], v[238:239], v[246:247]
	v_pk_mul_f32 v[240:241], v[240:241], v[248:249]
	v_pk_mul_f32 v[242:243], v[242:243], v[250:251]
	v_pk_mul_f32 v[236:237], v[4:5], v[236:237]
	v_pk_mul_f32 v[238:239], v[4:5], v[238:239]
	v_pk_mul_f32 v[240:241], v[4:5], v[240:241]
	v_pk_mul_f32 v[242:243], v[4:5], v[242:243]
	v_cvt_pk_bf16_f32 v228, v236, v237
	v_cvt_pk_bf16_f32 v229, v238, v239
	v_cvt_pk_bf16_f32 v230, v240, v241
	v_cvt_pk_bf16_f32 v231, v242, v243
	global_store_dwordx4 v8, v[228:231], s[30:31] offset:1664
	s_waitcnt vmcnt(17)
	v_lshlrev_b32_e32 v244, 16, v186
	v_and_b32_e32 v245, 0xffff0000, v186
	v_lshlrev_b32_e32 v246, 16, v187
	v_and_b32_e32 v247, 0xffff0000, v187
	v_lshlrev_b32_e32 v248, 16, v188
	v_and_b32_e32 v249, 0xffff0000, v188
	v_lshlrev_b32_e32 v250, 16, v189
	v_and_b32_e32 v251, 0xffff0000, v189
	v_mul_f32_e32 v252, v244, v244
	v_fmac_f32_e32 v252, v245, v245
	v_fmac_f32_e32 v252, v246, v246
	v_fmac_f32_e32 v252, v247, v247
	v_fmac_f32_e32 v252, v248, v248
	v_fmac_f32_e32 v252, v249, v249
	v_fmac_f32_e32 v252, v250, v250
	v_fmac_f32_e32 v252, v251, v251
	s_nop 1
	v_add_f32_dpp v252, v252, v252 quad_perm:[1,0,3,2] row_mask:0xf bank_mask:0xf bound_ctrl:1
	s_nop 1
	v_add_f32_dpp v252, v252, v252 quad_perm:[2,3,0,1] row_mask:0xf bank_mask:0xf bound_ctrl:1
	s_nop 1
	v_add_f32_dpp v252, v252, v252 row_half_mirror row_mask:0xf bank_mask:0xf bound_ctrl:1
	s_nop 1
	v_add_f32_dpp v252, v252, v252 row_mirror row_mask:0xf bank_mask:0xf bound_ctrl:1
	v_lshlrev_b32_e32 v186, 16, v190
	v_and_b32_e32 v187, 0xffff0000, v190
	v_lshlrev_b32_e32 v188, 16, v191
	v_and_b32_e32 v189, 0xffff0000, v191
	v_lshlrev_b32_e32 v190, 16, v192
	v_and_b32_e32 v191, 0xffff0000, v192
	v_lshlrev_b32_e32 v192, 16, v193
	v_and_b32_e32 v193, 0xffff0000, v193
	s_nop 0
	v_readlane_b32 s40, v252, 0
	v_readlane_b32 s41, v252, 16
	v_readlane_b32 s42, v252, 32
	v_readlane_b32 s43, v252, 48
	v_readlane_b32 s44, v253, 32
	v_pk_fma_f32 v[236:237], v[162:163], v[18:19], v[10:11]
	v_pk_fma_f32 v[238:239], v[164:165], v[20:21], v[12:13]
	v_pk_fma_f32 v[240:241], v[166:167], v[22:23], v[14:15]
	v_pk_fma_f32 v[242:243], v[168:169], v[24:25], v[16:17]
	v_pk_fma_f32 v[236:237], v[170:171], v[26:27], v[236:237]
	v_pk_fma_f32 v[238:239], v[172:173], v[28:29], v[238:239]
	v_pk_fma_f32 v[240:241], v[174:175], v[30:31], v[240:241]
	v_pk_fma_f32 v[242:243], v[176:177], v[32:33], v[242:243]
	v_pk_fma_f32 v[236:237], v[178:179], v[34:35], v[236:237]
	v_pk_fma_f32 v[238:239], v[180:181], v[36:37], v[238:239]
	v_pk_fma_f32 v[240:241], v[182:183], v[38:39], v[240:241]
	v_pk_fma_f32 v[242:243], v[184:185], v[40:41], v[242:243]
	v_pk_fma_f32 v[236:237], v[186:187], v[42:43], v[236:237]
	v_pk_fma_f32 v[238:239], v[188:189], v[44:45], v[238:239]
	v_pk_fma_f32 v[240:241], v[190:191], v[46:47], v[240:241]
	v_pk_fma_f32 v[242:243], v[192:193], v[48:49], v[242:243]
	v_writelane_b32 v218, s40, 14
	v_writelane_b32 v219, s41, 14
	v_writelane_b32 v220, s42, 14
	v_writelane_b32 v221, s43, 14
	v_writelane_b32 v222, s44, 14
	v_mul_f32_e32 v244, 0xbfb8aa3b, v236
	v_mul_f32_e32 v245, 0xbfb8aa3b, v237
	v_mul_f32_e32 v246, 0xbfb8aa3b, v238
	v_mul_f32_e32 v247, 0xbfb8aa3b, v239
	v_mul_f32_e32 v248, 0xbfb8aa3b, v240
	v_mul_f32_e32 v249, 0xbfb8aa3b, v241
	v_mul_f32_e32 v250, 0xbfb8aa3b, v242
	v_mul_f32_e32 v251, 0xbfb8aa3b, v243
	v_exp_f32_e32 v244, v244
	v_exp_f32_e32 v245, v245
	v_exp_f32_e32 v246, v246
	v_exp_f32_e32 v247, v247
	v_exp_f32_e32 v248, v248
	v_exp_f32_e32 v249, v249
	v_exp_f32_e32 v250, v250
	v_exp_f32_e32 v251, v251
	v_add_f32_e32 v244, 1.0, v244
	v_add_f32_e32 v245, 1.0, v245
	v_add_f32_e32 v246, 1.0, v246
	v_add_f32_e32 v247, 1.0, v247
	v_add_f32_e32 v248, 1.0, v248
	v_add_f32_e32 v249, 1.0, v249
	v_add_f32_e32 v250, 1.0, v250
	v_add_f32_e32 v251, 1.0, v251
	v_rcp_f32_e32 v244, v244
	v_rcp_f32_e32 v245, v245
	v_rcp_f32_e32 v246, v246
	v_rcp_f32_e32 v247, v247
	v_rcp_f32_e32 v248, v248
	v_rcp_f32_e32 v249, v249
	v_rcp_f32_e32 v250, v250
	v_rcp_f32_e32 v251, v251
	v_pk_mul_f32 v[236:237], v[236:237], v[244:245]
	v_pk_mul_f32 v[238:239], v[238:239], v[246:247]
	v_pk_mul_f32 v[240:241], v[240:241], v[248:249]
	v_pk_mul_f32 v[242:243], v[242:243], v[250:251]
	v_pk_mul_f32 v[236:237], v[4:5], v[236:237]
	v_pk_mul_f32 v[238:239], v[4:5], v[238:239]
	v_pk_mul_f32 v[240:241], v[4:5], v[240:241]
	v_pk_mul_f32 v[242:243], v[4:5], v[242:243]
	v_cvt_pk_bf16_f32 v224, v236, v237
	v_cvt_pk_bf16_f32 v225, v238, v239
	v_cvt_pk_bf16_f32 v226, v240, v241
	v_cvt_pk_bf16_f32 v227, v242, v243
	global_store_dwordx4 v8, v[224:227], s[30:31] offset:1792
	s_waitcnt vmcnt(16)
	v_lshlrev_b32_e32 v244, 16, v194
	v_and_b32_e32 v245, 0xffff0000, v194
	v_lshlrev_b32_e32 v246, 16, v195
	v_and_b32_e32 v247, 0xffff0000, v195
	v_lshlrev_b32_e32 v248, 16, v196
	v_and_b32_e32 v249, 0xffff0000, v196
	v_lshlrev_b32_e32 v250, 16, v197
	v_and_b32_e32 v251, 0xffff0000, v197
	v_mul_f32_e32 v252, v244, v244
	v_fmac_f32_e32 v252, v245, v245
	v_fmac_f32_e32 v252, v246, v246
	v_fmac_f32_e32 v252, v247, v247
	v_fmac_f32_e32 v252, v248, v248
	v_fmac_f32_e32 v252, v249, v249
	v_fmac_f32_e32 v252, v250, v250
	v_fmac_f32_e32 v252, v251, v251
	s_nop 1
	v_add_f32_dpp v252, v252, v252 quad_perm:[1,0,3,2] row_mask:0xf bank_mask:0xf bound_ctrl:1
	s_nop 1
	v_add_f32_dpp v252, v252, v252 quad_perm:[2,3,0,1] row_mask:0xf bank_mask:0xf bound_ctrl:1
	s_nop 1
	v_add_f32_dpp v252, v252, v252 row_half_mirror row_mask:0xf bank_mask:0xf bound_ctrl:1
	s_nop 1
	v_add_f32_dpp v252, v252, v252 row_mirror row_mask:0xf bank_mask:0xf bound_ctrl:1
	v_lshlrev_b32_e32 v194, 16, v198
	v_and_b32_e32 v195, 0xffff0000, v198
	v_lshlrev_b32_e32 v196, 16, v199
	v_and_b32_e32 v197, 0xffff0000, v199
	v_lshlrev_b32_e32 v198, 16, v200
	v_and_b32_e32 v199, 0xffff0000, v200
	v_lshlrev_b32_e32 v200, 16, v201
	v_and_b32_e32 v201, 0xffff0000, v201
	s_nop 0
	v_readlane_b32 s40, v252, 0
	v_readlane_b32 s41, v252, 16
	v_readlane_b32 s42, v252, 32
	v_readlane_b32 s43, v252, 48
	v_readlane_b32 s44, v253, 48
	v_pk_fma_f32 v[236:237], v[170:171], v[18:19], v[10:11]
	v_pk_fma_f32 v[238:239], v[172:173], v[20:21], v[12:13]
	v_pk_fma_f32 v[240:241], v[174:175], v[22:23], v[14:15]
	v_pk_fma_f32 v[242:243], v[176:177], v[24:25], v[16:17]
	v_pk_fma_f32 v[236:237], v[178:179], v[26:27], v[236:237]
	v_pk_fma_f32 v[238:239], v[180:181], v[28:29], v[238:239]
	v_pk_fma_f32 v[240:241], v[182:183], v[30:31], v[240:241]
	v_pk_fma_f32 v[242:243], v[184:185], v[32:33], v[242:243]
	v_pk_fma_f32 v[236:237], v[186:187], v[34:35], v[236:237]
	v_pk_fma_f32 v[238:239], v[188:189], v[36:37], v[238:239]
	v_pk_fma_f32 v[240:241], v[190:191], v[38:39], v[240:241]
	v_pk_fma_f32 v[242:243], v[192:193], v[40:41], v[242:243]
	v_pk_fma_f32 v[236:237], v[194:195], v[42:43], v[236:237]
	v_pk_fma_f32 v[238:239], v[196:197], v[44:45], v[238:239]
	v_pk_fma_f32 v[240:241], v[198:199], v[46:47], v[240:241]
	v_pk_fma_f32 v[242:243], v[200:201], v[48:49], v[242:243]
	v_writelane_b32 v218, s40, 15
	v_writelane_b32 v219, s41, 15
	v_writelane_b32 v220, s42, 15
	v_writelane_b32 v221, s43, 15
	v_writelane_b32 v222, s44, 15
	v_mul_f32_e32 v244, 0xbfb8aa3b, v236
	v_mul_f32_e32 v245, 0xbfb8aa3b, v237
	v_mul_f32_e32 v246, 0xbfb8aa3b, v238
	v_mul_f32_e32 v247, 0xbfb8aa3b, v239
	v_mul_f32_e32 v248, 0xbfb8aa3b, v240
	v_mul_f32_e32 v249, 0xbfb8aa3b, v241
	v_mul_f32_e32 v250, 0xbfb8aa3b, v242
	v_mul_f32_e32 v251, 0xbfb8aa3b, v243
	v_exp_f32_e32 v244, v244
	v_exp_f32_e32 v245, v245
	v_exp_f32_e32 v246, v246
	v_exp_f32_e32 v247, v247
	v_exp_f32_e32 v248, v248
	v_exp_f32_e32 v249, v249
	v_exp_f32_e32 v250, v250
	v_exp_f32_e32 v251, v251
	v_add_f32_e32 v244, 1.0, v244
	v_add_f32_e32 v245, 1.0, v245
	v_add_f32_e32 v246, 1.0, v246
	v_add_f32_e32 v247, 1.0, v247
	v_add_f32_e32 v248, 1.0, v248
	v_add_f32_e32 v249, 1.0, v249
	v_add_f32_e32 v250, 1.0, v250
	v_add_f32_e32 v251, 1.0, v251
	v_rcp_f32_e32 v244, v244
	v_rcp_f32_e32 v245, v245
	v_rcp_f32_e32 v246, v246
	v_rcp_f32_e32 v247, v247
	v_rcp_f32_e32 v248, v248
	v_rcp_f32_e32 v249, v249
	v_rcp_f32_e32 v250, v250
	v_rcp_f32_e32 v251, v251
	v_pk_mul_f32 v[236:237], v[236:237], v[244:245]
	v_pk_mul_f32 v[238:239], v[238:239], v[246:247]
	v_pk_mul_f32 v[240:241], v[240:241], v[248:249]
	v_pk_mul_f32 v[242:243], v[242:243], v[250:251]
	v_pk_mul_f32 v[236:237], v[4:5], v[236:237]
	v_pk_mul_f32 v[238:239], v[4:5], v[238:239]
	v_pk_mul_f32 v[240:241], v[4:5], v[240:241]
	v_pk_mul_f32 v[242:243], v[4:5], v[242:243]
	v_cvt_pk_bf16_f32 v228, v236, v237
	v_cvt_pk_bf16_f32 v229, v238, v239
	v_cvt_pk_bf16_f32 v230, v240, v241
	v_cvt_pk_bf16_f32 v231, v242, v243
	global_store_dwordx4 v8, v[228:231], s[30:31] offset:1920
	v_add_f32_e32 v218, v218, v219
	v_add_f32_e32 v221, v221, v222
	v_add_f32_e32 v218, v218, v220
	v_mov_b32_e32 v3, 0x358637bd
	v_fmamk_f32 v221, v221, 0x3b800000, v3
	v_fmamk_f32 v218, v218, 0x3b2aaaab, v3
	v_rsq_f32_e32 v221, v221
	v_rsq_f32_e32 v218, v218
	s_mov_b64 exec, 0xffff
	global_store_dword v9, v218, s[26:27]
	global_store_dword v9, v221, s[28:29]
	s_mov_b64 exec, -1
	s_add_i32 s20, s20, s21
	s_cmpk_lt_i32 s20, 0x7fff
	s_cbranch_scc1 .Lp3_block
